# v118 plus nt hint on final-phase x/out-projection loads and P0 weight-transpose loads (read once)
# speedup vs baseline: 1.0160x; 1.0017x over previous
; #define LAS __attribute__((address_space(3)))
; __device__ __forceinline__ void p0_transpose_item(const float* W, int ld, int K, int ncols, bf16* WT, LAS float* scr, int item, int lane) {
;     const int nblk = ncols / 32, kb = item / nblk, nb = item % nblk, k0 = 64 * kb, n0 = 32 * nb;
; #pragma unroll 8
;     for (int i = 0; i < 32; ++i) { const int kk = 2 * i + (lane >> 5); scr[kk * 33 + (lane & 31)] = W[(size_t)(k0 + kk) * ld + n0 + (lane & 31)]; }
.LBB0_20:
	s_lshl_b32 s27, s23, 1
	s_lshl_b32 s28, s24, 1
	v_or_b32_e32 v4, s28, v26
	s_add_i32 s30, s27, 4
	s_add_i32 s31, s28, 4
	v_mov_b32_e32 v35, v5
	s_add_i32 s34, s28, 8
	v_lshlrev_b64 v[48:49], 12, v[4:5]
	v_or_b32_e32 v34, s30, v3
	v_or_b32_e32 v4, s31, v26
	v_mov_b32_e32 v33, v5
	v_or_b32_e32 v32, s27, v3
	s_add_i32 s36, s28, 12
	v_lshlrev_b64 v[34:35], 12, v[34:35]
	v_lshlrev_b64 v[50:51], 12, v[4:5]
	v_or_b32_e32 v4, s34, v26
	s_add_i32 s33, s27, 8
	s_add_i32 s35, s27, 12
	s_add_i32 s38, s28, 16
	v_lshlrev_b64 v[32:33], 12, v[32:33]
	v_lshl_add_u64 v[48:49], v[24:25], 0, v[48:49]
	v_lshl_add_u64 v[34:35], v[24:25], 0, v[34:35]
	v_lshlrev_b64 v[52:53], 12, v[4:5]
	v_or_b32_e32 v4, s36, v26
	v_mov_b32_e32 v37, v5
	v_mov_b32_e32 v39, v5
	s_add_i32 s40, s28, 20
	v_or_b32_e32 v36, s33, v3
	v_or_b32_e32 v38, s35, v3
	v_lshl_add_u64 v[32:33], v[24:25], 0, v[32:33]
	v_lshl_add_u64 v[50:51], v[24:25], 0, v[50:51]
	global_load_dword v21, v[48:49], off nt
	global_load_dword v23, v[32:33], off nt
	global_load_dword v64, v[50:51], off nt
	global_load_dword v65, v[34:35], off nt
	v_lshlrev_b64 v[34:35], 12, v[4:5]
	v_or_b32_e32 v4, s38, v26
	s_add_i32 s37, s27, 16
	s_add_i32 s39, s27, 20
	s_add_i32 s42, s28, 24
	v_lshlrev_b64 v[36:37], 12, v[36:37]
	v_lshlrev_b64 v[38:39], 12, v[38:39]
	v_lshl_add_u64 v[32:33], v[24:25], 0, v[52:53]
	v_lshl_add_u64 v[34:35], v[24:25], 0, v[34:35]
	v_lshlrev_b64 v[48:49], 12, v[4:5]
	v_or_b32_e32 v4, s40, v26
	v_mov_b32_e32 v41, v5
	v_mov_b32_e32 v43, v5
	s_add_i32 s41, s27, 24
	s_add_i32 s43, s27, 28
	s_add_i32 s44, s28, 28
	v_or_b32_e32 v40, s37, v3
	v_or_b32_e32 v42, s39, v3
	v_lshl_add_u64 v[36:37], v[24:25], 0, v[36:37]
	v_lshl_add_u64 v[38:39], v[24:25], 0, v[38:39]
	global_load_dword v66, v[32:33], off nt
	global_load_dword v67, v[36:37], off nt
	global_load_dword v68, v[34:35], off nt
	global_load_dword v69, v[38:39], off nt
	v_lshlrev_b64 v[34:35], 12, v[4:5]
	v_or_b32_e32 v4, s42, v26
	v_mov_b32_e32 v45, v5
	v_mov_b32_e32 v47, v5
	v_or_b32_e32 v44, s41, v3
	v_or_b32_e32 v46, s43, v3
	v_lshlrev_b64 v[40:41], 12, v[40:41]
	v_lshlrev_b64 v[42:43], 12, v[42:43]
	v_lshl_add_u64 v[32:33], v[24:25], 0, v[48:49]
	v_lshl_add_u64 v[34:35], v[24:25], 0, v[34:35]
	v_lshlrev_b64 v[36:37], 12, v[4:5]
	v_or_b32_e32 v4, s44, v26
	v_lshlrev_b64 v[44:45], 12, v[44:45]
	v_lshlrev_b64 v[46:47], 12, v[46:47]
	v_lshl_add_u64 v[40:41], v[24:25], 0, v[40:41]
	v_lshl_add_u64 v[42:43], v[24:25], 0, v[42:43]
	global_load_dword v70, v[32:33], off nt
	global_load_dword v71, v[40:41], off nt
	global_load_dword v72, v[34:35], off nt
	global_load_dword v73, v[42:43], off nt
	v_lshl_add_u64 v[32:33], v[24:25], 0, v[36:37]
	v_lshlrev_b64 v[34:35], 12, v[4:5]
	v_lshl_add_u64 v[44:45], v[24:25], 0, v[44:45]
	v_lshl_add_u64 v[46:47], v[24:25], 0, v[46:47]
	v_lshl_add_u64 v[34:35], v[24:25], 0, v[34:35]
	global_load_dword v4, v[32:33], off nt
	global_load_dword v74, v[44:45], off nt
	global_load_dword v75, v[34:35], off nt
	global_load_dword v76, v[46:47], off nt
	v_or_b32_e32 v34, s27, v1
	v_or_b32_e32 v32, s28, v2
	s_add_i32 s24, s24, 16
	s_add_i32 s23, s23, 16
	s_add_i32 s25, s25, -16
	v_mad_u64_u32 v[32:33], s[28:29], v32, s13, v[8:9]
	v_mad_u64_u32 v[34:35], s[28:29], v34, s13, v[8:9]
	v_or_b32_e32 v33, s30, v1
	v_or_b32_e32 v35, s31, v2
	v_or_b32_e32 v42, s33, v1
	v_or_b32_e32 v40, s34, v2
	v_or_b32_e32 v46, s35, v1
	v_or_b32_e32 v44, s36, v2
	v_or_b32_e32 v50, s37, v1
	v_or_b32_e32 v48, s38, v2
	v_or_b32_e32 v54, s39, v1
	v_or_b32_e32 v52, s40, v2
	v_or_b32_e32 v58, s41, v1
	v_or_b32_e32 v56, s42, v2
	v_or_b32_e32 v62, s43, v1
	v_or_b32_e32 v60, s44, v2
	s_cmp_lg_u32 s25, 0
	v_mad_u64_u32 v[36:37], s[28:29], v35, s13, v[8:9]
	v_mad_u64_u32 v[38:39], s[28:29], v33, s13, v[8:9]
	v_mad_u64_u32 v[40:41], s[28:29], v40, s13, v[8:9]
	v_mad_u64_u32 v[42:43], s[28:29], v42, s13, v[8:9]
	v_mad_u64_u32 v[44:45], s[28:29], v44, s13, v[8:9]
	v_mad_u64_u32 v[46:47], s[28:29], v46, s13, v[8:9]
	v_mad_u64_u32 v[48:49], s[28:29], v48, s13, v[8:9]
	v_mad_u64_u32 v[50:51], s[28:29], v50, s13, v[8:9]
	v_mad_u64_u32 v[52:53], s[28:29], v52, s13, v[8:9]
	v_mad_u64_u32 v[54:55], s[28:29], v54, s13, v[8:9]
	v_mad_u64_u32 v[56:57], s[28:29], v56, s13, v[8:9]
	v_mad_u64_u32 v[58:59], s[28:29], v58, s13, v[8:9]
	v_mad_u64_u32 v[60:61], s[28:29], v60, s13, v[8:9]
	v_mad_u64_u32 v[62:63], s[28:29], v62, s13, v[8:9]
	s_waitcnt vmcnt(15)
	ds_write_b32 v32, v21
	s_waitcnt vmcnt(14)
	ds_write_b32 v34, v23
	s_waitcnt vmcnt(13)
	ds_write_b32 v36, v64
	s_waitcnt vmcnt(12)
	ds_write_b32 v38, v65
	s_waitcnt vmcnt(11)
	ds_write_b32 v40, v66
	s_waitcnt vmcnt(10)
	ds_write_b32 v42, v67
	s_waitcnt vmcnt(9)
	ds_write_b32 v44, v68
	s_waitcnt vmcnt(8)
	ds_write_b32 v46, v69
	s_waitcnt vmcnt(7)
	ds_write_b32 v48, v70
	s_waitcnt vmcnt(6)
	ds_write_b32 v50, v71
	s_waitcnt vmcnt(5)
	ds_write_b32 v52, v72
	s_waitcnt vmcnt(4)
	ds_write_b32 v54, v73
	s_waitcnt vmcnt(3)
	ds_write_b32 v56, v4
	s_waitcnt vmcnt(2)
	ds_write_b32 v58, v74
	s_waitcnt vmcnt(1)
	ds_write_b32 v60, v75
	s_waitcnt vmcnt(0)
	ds_write_b32 v62, v76
	s_cbranch_scc1 .LBB0_20
; #define GAS __attribute__((address_space(1)))
; #define LAS __attribute__((address_space(3)))
; #define LDS_WAIT() asm volatile("s_waitcnt lgkmcnt(0)" ::: "memory")
; __device__ __forceinline__ unsigned pk2(float lo, float hi) { return f2bf(lo) | (f2bf(hi) << 16); }
; __device__ __forceinline__ void p0_transpose_item(const float* W, int ld, int K, int ncols, bf16* WT, LAS float* scr, int item, int lane) {
;     ...
;     const int c = lane & 7;
; #pragma unroll
;     for (int j = 0; j < 4; ++j) { const int n = (lane >> 3) + 8 * j; const LAS float* s = scr + (8 * c) * 33 + n;
;         v4u o; o.x = pk2(s[0 * 33], s[1 * 33]); o.y = pk2(s[2 * 33], s[3 * 33]); o.z = pk2(s[4 * 33], s[5 * 33]); o.w = pk2(s[6 * 33], s[7 * 33]);
;         *(GAS v4u*)(WT + (size_t)(n0 + n) * K + k0 + 8 * c) = o; }
;     LDS_WAIT(); asm volatile("" ::: "memory");
	s_waitcnt lgkmcnt(0)
	ds_read2_b32 v[24:25], v28 offset1:8
	ds_read2_b32 v[38:39], v28 offset0:33 offset1:41
	ds_read2_b32 v[40:41], v28 offset0:66 offset1:74
	ds_read2_b32 v[42:43], v28 offset0:99 offset1:107
	ds_read2_b32 v[44:45], v28 offset0:132 offset1:140
	ds_read2_b32 v[46:47], v28 offset0:165 offset1:173
	s_waitcnt lgkmcnt(5)
	v_bfe_u32 v3, v24, 16, 1
	v_add3_u32 v3, v24, v3, s15
	s_waitcnt lgkmcnt(4)
	v_bfe_u32 v4, v38, 16, 1
	v_lshrrev_b32_e32 v3, 16, v3
	v_add3_u32 v4, v38, v4, s15
	v_and_or_b32 v32, v4, s16, v3
	s_waitcnt lgkmcnt(3)
	v_bfe_u32 v3, v40, 16, 1
	v_add3_u32 v3, v40, v3, s15
	s_waitcnt lgkmcnt(2)
	v_bfe_u32 v4, v42, 16, 1
	ds_read2_b32 v[48:49], v28 offset0:198 offset1:206
	v_lshrrev_b32_e32 v3, 16, v3
	v_add3_u32 v4, v42, v4, s15
	ds_read2_b32 v[50:51], v28 offset0:231 offset1:239
	v_and_or_b32 v33, v4, s16, v3
	s_waitcnt lgkmcnt(3)
	v_bfe_u32 v3, v44, 16, 1
	v_add3_u32 v3, v44, v3, s15
	s_waitcnt lgkmcnt(2)
	v_bfe_u32 v4, v46, 16, 1
	v_lshrrev_b32_e32 v3, 16, v3
	v_add3_u32 v4, v46, v4, s15
	v_and_or_b32 v34, v4, s16, v3
	s_waitcnt lgkmcnt(1)
	v_bfe_u32 v3, v48, 16, 1
	v_add3_u32 v3, v48, v3, s15
	s_waitcnt lgkmcnt(0)
	v_bfe_u32 v4, v50, 16, 1
	v_lshrrev_b32_e32 v3, 16, v3
	v_add3_u32 v4, v50, v4, s15
	s_lshl_b32 s6, s6, 1
	v_and_or_b32 v35, v4, s16, v3
	v_or_b32_e32 v3, s22, v27
	v_lshl_add_u64 v[36:37], v[10:11], 0, s[6:7]
	v_lshlrev_b32_e32 v4, 11, v3
	v_bfe_u32 v3, v25, 16, 1
	v_lshl_add_u64 v[52:53], v[36:37], 0, v[4:5]
	v_add3_u32 v3, v25, v3, s15
	v_bfe_u32 v4, v39, 16, 1
	v_lshrrev_b32_e32 v3, 16, v3
	v_add3_u32 v4, v39, v4, s15
	global_store_dwordx4 v[52:53], v[32:35], off
	ds_read2_b32 v[24:25], v28 offset0:16 offset1:24
	s_nop 0
	v_and_or_b32 v32, v4, s16, v3
	v_bfe_u32 v3, v41, 16, 1
	v_add3_u32 v3, v41, v3, s15
	v_bfe_u32 v4, v43, 16, 1
	v_lshrrev_b32_e32 v3, 16, v3
	v_add3_u32 v4, v43, v4, s15
	v_and_or_b32 v33, v4, s16, v3
	v_bfe_u32 v3, v45, 16, 1
	v_add3_u32 v3, v45, v3, s15
	v_bfe_u32 v4, v47, 16, 1
	v_lshrrev_b32_e32 v3, 16, v3
	v_add3_u32 v4, v47, v4, s15
	v_and_or_b32 v34, v4, s16, v3
	v_bfe_u32 v3, v49, 16, 1
	v_add3_u32 v3, v49, v3, s15
	v_bfe_u32 v4, v51, 16, 1
	v_lshrrev_b32_e32 v3, 16, v3
	v_add3_u32 v4, v51, v4, s15
	v_and_or_b32 v35, v4, s16, v3
	v_or_b32_e32 v3, s22, v29
	v_lshlrev_b32_e32 v4, 11, v3
	v_lshl_add_u64 v[38:39], v[36:37], 0, v[4:5]
	global_store_dwordx4 v[38:39], v[32:35], off
	ds_read2_b32 v[38:39], v28 offset0:49 offset1:57
	ds_read2_b32 v[40:41], v28 offset0:82 offset1:90
	ds_read2_b32 v[42:43], v28 offset0:115 offset1:123
	s_waitcnt lgkmcnt(3)
	v_bfe_u32 v3, v24, 16, 1
	v_add3_u32 v3, v24, v3, s15
	s_waitcnt lgkmcnt(2)
	v_bfe_u32 v4, v38, 16, 1
	ds_read2_b32 v[44:45], v28 offset0:148 offset1:156
	v_lshrrev_b32_e32 v3, 16, v3
	v_add3_u32 v4, v38, v4, s15
	ds_read2_b32 v[46:47], v28 offset0:181 offset1:189
	v_and_or_b32 v32, v4, s16, v3
	s_waitcnt lgkmcnt(3)
	v_bfe_u32 v3, v40, 16, 1
	v_add3_u32 v3, v40, v3, s15
	s_waitcnt lgkmcnt(2)
	v_bfe_u32 v4, v42, 16, 1
	ds_read2_b32 v[48:49], v28 offset0:214 offset1:222
	v_lshrrev_b32_e32 v3, 16, v3
	v_add3_u32 v4, v42, v4, s15
	ds_read2_b32 v[50:51], v28 offset0:247 offset1:255
	v_and_or_b32 v33, v4, s16, v3
	s_waitcnt lgkmcnt(3)
	v_bfe_u32 v3, v44, 16, 1
	v_add3_u32 v3, v44, v3, s15
	s_waitcnt lgkmcnt(2)
	v_bfe_u32 v4, v46, 16, 1
	v_lshrrev_b32_e32 v3, 16, v3
	v_add3_u32 v4, v46, v4, s15
	v_and_or_b32 v34, v4, s16, v3
	s_waitcnt lgkmcnt(1)
	v_bfe_u32 v3, v48, 16, 1
	v_add3_u32 v3, v48, v3, s15
	s_waitcnt lgkmcnt(0)
	v_bfe_u32 v4, v50, 16, 1
	v_lshrrev_b32_e32 v3, 16, v3
	v_add3_u32 v4, v50, v4, s15
	v_and_or_b32 v35, v4, s16, v3
	v_or_b32_e32 v3, s22, v30
	v_lshlrev_b32_e32 v4, 11, v3
	v_bfe_u32 v3, v25, 16, 1
	v_lshl_add_u64 v[52:53], v[36:37], 0, v[4:5]
	v_add3_u32 v3, v25, v3, s15
	v_bfe_u32 v4, v39, 16, 1
	v_lshrrev_b32_e32 v3, 16, v3
	v_add3_u32 v4, v39, v4, s15
	global_store_dwordx4 v[52:53], v[32:35], off
	s_nop 1
	v_and_or_b32 v32, v4, s16, v3
	v_bfe_u32 v3, v41, 16, 1
	v_add3_u32 v3, v41, v3, s15
	v_bfe_u32 v4, v43, 16, 1
	v_lshrrev_b32_e32 v3, 16, v3
	v_add3_u32 v4, v43, v4, s15
	v_and_or_b32 v33, v4, s16, v3
	v_bfe_u32 v3, v45, 16, 1
	v_add3_u32 v3, v45, v3, s15
	v_bfe_u32 v4, v47, 16, 1
	v_lshrrev_b32_e32 v3, 16, v3
	v_add3_u32 v4, v47, v4, s15
	v_and_or_b32 v34, v4, s16, v3
	v_bfe_u32 v3, v49, 16, 1
	v_add3_u32 v3, v49, v3, s15
	v_bfe_u32 v4, v51, 16, 1
	v_lshrrev_b32_e32 v3, 16, v3
	v_add3_u32 v4, v51, v4, s15
	v_and_or_b32 v35, v4, s16, v3
	v_or_b32_e32 v3, s22, v31
	v_lshlrev_b32_e32 v4, 11, v3
	v_lshl_add_u64 v[24:25], v[36:37], 0, v[4:5]
	global_store_dwordx4 v[24:25], v[32:35], off
	s_waitcnt lgkmcnt(0)
	s_mov_b64 s[22:23], 0

; #define LAS __attribute__((address_space(3)))
; __device__ __forceinline__ void p0_transpose_item(const float* W, int ld, int K, int ncols, bf16* WT, LAS float* scr, int item, int lane) {
;     const int nblk = ncols / 32, kb = item / nblk, nb = item % nblk, k0 = 64 * kb, n0 = 32 * nb;
; #pragma unroll 8
;     for (int i = 0; i < 32; ++i) { const int kk = 2 * i + (lane >> 5); scr[kk * 33 + (lane & 31)] = W[(size_t)(k0 + kk) * ld + n0 + (lane & 31)]; }
.LBB0_24:
	s_lshl_b32 s29, s25, 1
	s_lshl_b32 s30, s27, 1
	v_or_b32_e32 v4, s30, v26
	s_add_i32 s33, s29, 4
	s_add_i32 s34, s30, 4
	v_mov_b32_e32 v35, v5
	s_add_i32 s36, s30, 8
	v_lshlrev_b64 v[48:49], 12, v[4:5]
	v_or_b32_e32 v34, s33, v3
	v_or_b32_e32 v4, s34, v26
	v_mov_b32_e32 v33, v5
	v_or_b32_e32 v32, s29, v3
	s_add_i32 s38, s30, 12
	v_lshlrev_b64 v[34:35], 12, v[34:35]
	v_lshlrev_b64 v[50:51], 12, v[4:5]
	v_or_b32_e32 v4, s36, v26
	s_add_i32 s35, s29, 8
	s_add_i32 s37, s29, 12
	s_add_i32 s40, s30, 16
	v_lshlrev_b64 v[32:33], 12, v[32:33]
	v_lshl_add_u64 v[48:49], v[24:25], 0, v[48:49]
	v_lshl_add_u64 v[34:35], v[24:25], 0, v[34:35]
	v_lshlrev_b64 v[52:53], 12, v[4:5]
	v_or_b32_e32 v4, s38, v26
	v_mov_b32_e32 v37, v5
	v_mov_b32_e32 v39, v5
	s_add_i32 s42, s30, 20
	v_or_b32_e32 v36, s35, v3
	v_or_b32_e32 v38, s37, v3
	v_lshl_add_u64 v[32:33], v[24:25], 0, v[32:33]
	v_lshl_add_u64 v[50:51], v[24:25], 0, v[50:51]
	global_load_dword v21, v[48:49], off nt
	global_load_dword v23, v[32:33], off nt
	global_load_dword v64, v[50:51], off nt
	global_load_dword v65, v[34:35], off nt
	v_lshlrev_b64 v[34:35], 12, v[4:5]
	v_or_b32_e32 v4, s40, v26
	s_add_i32 s39, s29, 16
	s_add_i32 s41, s29, 20
	s_add_i32 s44, s30, 24
	v_lshlrev_b64 v[36:37], 12, v[36:37]
	v_lshlrev_b64 v[38:39], 12, v[38:39]
	v_lshl_add_u64 v[32:33], v[24:25], 0, v[52:53]
	v_lshl_add_u64 v[34:35], v[24:25], 0, v[34:35]
	v_lshlrev_b64 v[48:49], 12, v[4:5]
	v_or_b32_e32 v4, s42, v26
	v_mov_b32_e32 v41, v5
	v_mov_b32_e32 v43, v5
	s_add_i32 s43, s29, 24
	s_add_i32 s45, s29, 28
	s_add_i32 s46, s30, 28
	v_or_b32_e32 v40, s39, v3
	v_or_b32_e32 v42, s41, v3
	v_lshl_add_u64 v[36:37], v[24:25], 0, v[36:37]
	v_lshl_add_u64 v[38:39], v[24:25], 0, v[38:39]
	global_load_dword v66, v[32:33], off nt
	global_load_dword v67, v[36:37], off nt
	global_load_dword v68, v[34:35], off nt
	global_load_dword v69, v[38:39], off nt
	v_lshlrev_b64 v[34:35], 12, v[4:5]
	v_or_b32_e32 v4, s44, v26
	v_mov_b32_e32 v45, v5
	v_mov_b32_e32 v47, v5
	v_or_b32_e32 v44, s43, v3
	v_or_b32_e32 v46, s45, v3
	v_lshlrev_b64 v[40:41], 12, v[40:41]
	v_lshlrev_b64 v[42:43], 12, v[42:43]
	v_lshl_add_u64 v[32:33], v[24:25], 0, v[48:49]
	v_lshl_add_u64 v[34:35], v[24:25], 0, v[34:35]
	v_lshlrev_b64 v[36:37], 12, v[4:5]
	v_or_b32_e32 v4, s46, v26
	v_lshlrev_b64 v[44:45], 12, v[44:45]
	v_lshlrev_b64 v[46:47], 12, v[46:47]
	v_lshl_add_u64 v[40:41], v[24:25], 0, v[40:41]
	v_lshl_add_u64 v[42:43], v[24:25], 0, v[42:43]
	global_load_dword v70, v[32:33], off nt
	global_load_dword v71, v[40:41], off nt
	global_load_dword v72, v[34:35], off nt
	global_load_dword v73, v[42:43], off nt
	v_lshl_add_u64 v[32:33], v[24:25], 0, v[36:37]
	v_lshlrev_b64 v[34:35], 12, v[4:5]
	v_lshl_add_u64 v[44:45], v[24:25], 0, v[44:45]
	v_lshl_add_u64 v[46:47], v[24:25], 0, v[46:47]
	v_lshl_add_u64 v[34:35], v[24:25], 0, v[34:35]
	global_load_dword v4, v[32:33], off nt
	global_load_dword v74, v[44:45], off nt
	global_load_dword v75, v[34:35], off nt
	global_load_dword v76, v[46:47], off nt
	v_or_b32_e32 v34, s29, v1
	v_or_b32_e32 v32, s30, v2
	s_add_i32 s27, s27, 16
	s_add_i32 s25, s25, 16
	s_add_i32 s28, s28, -16
	v_mad_u64_u32 v[32:33], s[30:31], v32, s13, v[8:9]
	v_mad_u64_u32 v[34:35], s[30:31], v34, s13, v[8:9]
	v_or_b32_e32 v33, s33, v1
	v_or_b32_e32 v35, s34, v2
	v_or_b32_e32 v42, s35, v1
	v_or_b32_e32 v40, s36, v2
	v_or_b32_e32 v46, s37, v1
	v_or_b32_e32 v44, s38, v2
	v_or_b32_e32 v50, s39, v1
	v_or_b32_e32 v48, s40, v2
	v_or_b32_e32 v54, s41, v1
	v_or_b32_e32 v52, s42, v2
	v_or_b32_e32 v58, s43, v1
	v_or_b32_e32 v56, s44, v2
	v_or_b32_e32 v62, s45, v1
	v_or_b32_e32 v60, s46, v2
	s_cmp_lg_u32 s28, 0
	v_mad_u64_u32 v[36:37], s[30:31], v35, s13, v[8:9]
	v_mad_u64_u32 v[38:39], s[30:31], v33, s13, v[8:9]
	v_mad_u64_u32 v[40:41], s[30:31], v40, s13, v[8:9]
	v_mad_u64_u32 v[42:43], s[30:31], v42, s13, v[8:9]
	v_mad_u64_u32 v[44:45], s[30:31], v44, s13, v[8:9]
	v_mad_u64_u32 v[46:47], s[30:31], v46, s13, v[8:9]
	v_mad_u64_u32 v[48:49], s[30:31], v48, s13, v[8:9]
	v_mad_u64_u32 v[50:51], s[30:31], v50, s13, v[8:9]
	v_mad_u64_u32 v[52:53], s[30:31], v52, s13, v[8:9]
	v_mad_u64_u32 v[54:55], s[30:31], v54, s13, v[8:9]
	v_mad_u64_u32 v[56:57], s[30:31], v56, s13, v[8:9]
	v_mad_u64_u32 v[58:59], s[30:31], v58, s13, v[8:9]
	v_mad_u64_u32 v[60:61], s[30:31], v60, s13, v[8:9]
	v_mad_u64_u32 v[62:63], s[30:31], v62, s13, v[8:9]
	s_waitcnt vmcnt(15)
	ds_write_b32 v32, v21
	s_waitcnt vmcnt(14)
	ds_write_b32 v34, v23
	s_waitcnt vmcnt(13)
	ds_write_b32 v36, v64
	s_waitcnt vmcnt(12)
	ds_write_b32 v38, v65
	s_waitcnt vmcnt(11)
	ds_write_b32 v40, v66
	s_waitcnt vmcnt(10)
	ds_write_b32 v42, v67
	s_waitcnt vmcnt(9)
	ds_write_b32 v44, v68
	s_waitcnt vmcnt(8)
	ds_write_b32 v46, v69
	s_waitcnt vmcnt(7)
	ds_write_b32 v48, v70
	s_waitcnt vmcnt(6)
	ds_write_b32 v50, v71
	s_waitcnt vmcnt(5)
	ds_write_b32 v52, v72
	s_waitcnt vmcnt(4)
	ds_write_b32 v54, v73
	s_waitcnt vmcnt(3)
	ds_write_b32 v56, v4
	s_waitcnt vmcnt(2)
	ds_write_b32 v58, v74
	s_waitcnt vmcnt(1)
	ds_write_b32 v60, v75
	s_waitcnt vmcnt(0)
	ds_write_b32 v62, v76
	s_cbranch_scc1 .LBB0_24
; #define GAS __attribute__((address_space(1)))
; #define LAS __attribute__((address_space(3)))
; #define LDS_WAIT() asm volatile("s_waitcnt lgkmcnt(0)" ::: "memory")
; __device__ __forceinline__ unsigned pk2(float lo, float hi) { return f2bf(lo) | (f2bf(hi) << 16); }
; __device__ __forceinline__ void p0_transpose_item(const float* W, int ld, int K, int ncols, bf16* WT, LAS float* scr, int item, int lane) {
;     ...
;     LDS_WAIT(); asm volatile("" ::: "memory");
;     const int c = lane & 7;
; #pragma unroll
;     for (int j = 0; j < 4; ++j) { const int n = (lane >> 3) + 8 * j; const LAS float* s = scr + (8 * c) * 33 + n;
;         v4u o; o.x = pk2(s[0 * 33], s[1 * 33]); o.y = pk2(s[2 * 33], s[3 * 33]); o.z = pk2(s[4 * 33], s[5 * 33]); o.w = pk2(s[6 * 33], s[7 * 33]);
;         *(GAS v4u*)(WT + (size_t)(n0 + n) * K + k0 + 8 * c) = o; }
;     LDS_WAIT(); asm volatile("" ::: "memory");
	s_waitcnt lgkmcnt(0)
	ds_read2_b32 v[24:25], v28 offset1:8
	ds_read2_b32 v[38:39], v28 offset0:33 offset1:41
	ds_read2_b32 v[40:41], v28 offset0:66 offset1:74
	ds_read2_b32 v[42:43], v28 offset0:99 offset1:107
	ds_read2_b32 v[44:45], v28 offset0:132 offset1:140
	s_waitcnt lgkmcnt(4)
	v_bfe_u32 v3, v24, 16, 1
	v_add3_u32 v3, v24, v3, s15
	s_waitcnt lgkmcnt(3)
	v_bfe_u32 v4, v38, 16, 1
	v_lshrrev_b32_e32 v3, 16, v3
	v_add3_u32 v4, v38, v4, s15
	ds_read2_b32 v[46:47], v28 offset0:165 offset1:173
	v_and_or_b32 v32, v4, s16, v3
	s_waitcnt lgkmcnt(3)
	v_bfe_u32 v3, v40, 16, 1
	v_add3_u32 v3, v40, v3, s15
	s_waitcnt lgkmcnt(2)
	v_bfe_u32 v4, v42, 16, 1
	ds_read2_b32 v[48:49], v28 offset0:198 offset1:206
	v_lshrrev_b32_e32 v3, 16, v3
	v_add3_u32 v4, v42, v4, s15
	ds_read2_b32 v[50:51], v28 offset0:231 offset1:239
	v_and_or_b32 v33, v4, s16, v3
	s_waitcnt lgkmcnt(3)
	v_bfe_u32 v3, v44, 16, 1
	v_add3_u32 v3, v44, v3, s15
	s_waitcnt lgkmcnt(2)
	v_bfe_u32 v4, v46, 16, 1
	s_lshl_b64 s[22:23], s[22:23], 1
	v_lshrrev_b32_e32 v3, 16, v3
	v_add3_u32 v4, v46, v4, s15
	s_add_u32 s22, s2, s22
	v_and_or_b32 v34, v4, s16, v3
	s_waitcnt lgkmcnt(1)
	v_bfe_u32 v3, v48, 16, 1
	s_addc_u32 s23, s3, s23
	s_lshl_b32 s24, s24, 1
	v_add3_u32 v3, v48, v3, s15
	s_waitcnt lgkmcnt(0)
	v_bfe_u32 v4, v50, 16, 1
	s_add_u32 s22, s22, s24
	v_lshrrev_b32_e32 v3, 16, v3
	v_add3_u32 v4, v50, v4, s15
	s_addc_u32 s23, s23, 0
	v_mov_b32_e32 v21, v5
	v_and_or_b32 v35, v4, s16, v3
	v_or_b32_e32 v3, s6, v27
	v_lshl_add_u64 v[36:37], s[22:23], 0, v[20:21]
	v_lshlrev_b32_e32 v4, 11, v3
	v_bfe_u32 v3, v25, 16, 1
	v_lshl_add_u64 v[52:53], v[36:37], 0, v[4:5]
	v_add3_u32 v3, v25, v3, s15
	v_bfe_u32 v4, v39, 16, 1
	v_lshrrev_b32_e32 v3, 16, v3
	v_add3_u32 v4, v39, v4, s15
	global_store_dwordx4 v[52:53], v[32:35], off
	ds_read2_b32 v[24:25], v28 offset0:16 offset1:24
	s_nop 0
	v_and_or_b32 v32, v4, s16, v3
	v_bfe_u32 v3, v41, 16, 1
	v_add3_u32 v3, v41, v3, s15
	v_bfe_u32 v4, v43, 16, 1
	v_lshrrev_b32_e32 v3, 16, v3
	v_add3_u32 v4, v43, v4, s15
	v_and_or_b32 v33, v4, s16, v3
	v_bfe_u32 v3, v45, 16, 1
	v_add3_u32 v3, v45, v3, s15
	v_bfe_u32 v4, v47, 16, 1
	v_lshrrev_b32_e32 v3, 16, v3
	v_add3_u32 v4, v47, v4, s15
	v_and_or_b32 v34, v4, s16, v3
	v_bfe_u32 v3, v49, 16, 1
	v_add3_u32 v3, v49, v3, s15
	v_bfe_u32 v4, v51, 16, 1
	v_lshrrev_b32_e32 v3, 16, v3
	v_add3_u32 v4, v51, v4, s15
	v_and_or_b32 v35, v4, s16, v3
	v_or_b32_e32 v3, s6, v29
	v_lshlrev_b32_e32 v4, 11, v3
	v_lshl_add_u64 v[38:39], v[36:37], 0, v[4:5]
	global_store_dwordx4 v[38:39], v[32:35], off
	ds_read2_b32 v[38:39], v28 offset0:49 offset1:57
	ds_read2_b32 v[40:41], v28 offset0:82 offset1:90
	ds_read2_b32 v[42:43], v28 offset0:115 offset1:123
	s_waitcnt lgkmcnt(3)
	v_bfe_u32 v3, v24, 16, 1
	v_add3_u32 v3, v24, v3, s15
	s_waitcnt lgkmcnt(2)
	v_bfe_u32 v4, v38, 16, 1
	ds_read2_b32 v[44:45], v28 offset0:148 offset1:156
	v_lshrrev_b32_e32 v3, 16, v3
	v_add3_u32 v4, v38, v4, s15
	ds_read2_b32 v[46:47], v28 offset0:181 offset1:189
	v_and_or_b32 v32, v4, s16, v3
	s_waitcnt lgkmcnt(3)
	v_bfe_u32 v3, v40, 16, 1
	v_add3_u32 v3, v40, v3, s15
	s_waitcnt lgkmcnt(2)
	v_bfe_u32 v4, v42, 16, 1
	ds_read2_b32 v[48:49], v28 offset0:214 offset1:222
	v_lshrrev_b32_e32 v3, 16, v3
	v_add3_u32 v4, v42, v4, s15
	ds_read2_b32 v[50:51], v28 offset0:247 offset1:255
	v_and_or_b32 v33, v4, s16, v3
	s_waitcnt lgkmcnt(3)
	v_bfe_u32 v3, v44, 16, 1
	v_add3_u32 v3, v44, v3, s15
	s_waitcnt lgkmcnt(2)
	v_bfe_u32 v4, v46, 16, 1
	v_lshrrev_b32_e32 v3, 16, v3
	v_add3_u32 v4, v46, v4, s15
	v_and_or_b32 v34, v4, s16, v3
	s_waitcnt lgkmcnt(1)
	v_bfe_u32 v3, v48, 16, 1
	v_add3_u32 v3, v48, v3, s15
	s_waitcnt lgkmcnt(0)
	v_bfe_u32 v4, v50, 16, 1
	v_lshrrev_b32_e32 v3, 16, v3
	v_add3_u32 v4, v50, v4, s15
	v_and_or_b32 v35, v4, s16, v3
	v_or_b32_e32 v3, s6, v30
	v_lshlrev_b32_e32 v4, 11, v3
	v_bfe_u32 v3, v25, 16, 1
	v_lshl_add_u64 v[52:53], v[36:37], 0, v[4:5]
	v_add3_u32 v3, v25, v3, s15
	v_bfe_u32 v4, v39, 16, 1
	v_lshrrev_b32_e32 v3, 16, v3
	v_add3_u32 v4, v39, v4, s15
	global_store_dwordx4 v[52:53], v[32:35], off
	s_nop 1
	v_and_or_b32 v32, v4, s16, v3
	v_bfe_u32 v3, v41, 16, 1
	v_add3_u32 v3, v41, v3, s15
	v_bfe_u32 v4, v43, 16, 1
	v_lshrrev_b32_e32 v3, 16, v3
	v_add3_u32 v4, v43, v4, s15
	v_and_or_b32 v33, v4, s16, v3
	v_bfe_u32 v3, v45, 16, 1
	v_add3_u32 v3, v45, v3, s15
	v_bfe_u32 v4, v47, 16, 1
	v_lshrrev_b32_e32 v3, 16, v3
	v_add3_u32 v4, v47, v4, s15
	v_and_or_b32 v34, v4, s16, v3
	v_bfe_u32 v3, v49, 16, 1
	v_add3_u32 v3, v49, v3, s15
	v_bfe_u32 v4, v51, 16, 1
	v_lshrrev_b32_e32 v3, 16, v3
	v_add3_u32 v4, v51, v4, s15
	v_and_or_b32 v35, v4, s16, v3
	v_or_b32_e32 v3, s6, v31
	v_lshlrev_b32_e32 v4, 11, v3
	v_lshl_add_u64 v[24:25], v[36:37], 0, v[4:5]
	global_store_dwordx4 v[24:25], v[32:35], off
	s_waitcnt lgkmcnt(0)

; #define LAS __attribute__((address_space(3)))
; __device__ __forceinline__ void p0_transpose_item(const float* W, int ld, int K, int ncols, bf16* WT, LAS float* scr, int item, int lane) {
;     const int nblk = ncols / 32, kb = item / nblk, nb = item % nblk, k0 = 64 * kb, n0 = 32 * nb;
; #pragma unroll 8
;     for (int i = 0; i < 32; ++i) { const int kk = 2 * i + (lane >> 5); scr[kk * 33 + (lane & 31)] = W[(size_t)(k0 + kk) * ld + n0 + (lane & 31)]; }
.LBB0_29:
	s_lshl_b32 s27, s23, 1
	s_lshl_b32 s28, s24, 1
	v_or_b32_e32 v4, s28, v26
	s_add_i32 s30, s27, 4
	s_add_i32 s31, s28, 4
	v_mov_b32_e32 v35, v5
	s_add_i32 s34, s28, 8
	v_lshlrev_b64 v[48:49], 12, v[4:5]
	v_or_b32_e32 v34, s30, v3
	v_or_b32_e32 v4, s31, v26
	v_mov_b32_e32 v33, v5
	v_or_b32_e32 v32, s27, v3
	s_add_i32 s36, s28, 12
	v_lshlrev_b64 v[34:35], 12, v[34:35]
	v_lshlrev_b64 v[50:51], 12, v[4:5]
	v_or_b32_e32 v4, s34, v26
	s_add_i32 s33, s27, 8
	s_add_i32 s35, s27, 12
	s_add_i32 s38, s28, 16
	v_lshlrev_b64 v[32:33], 12, v[32:33]
	v_lshl_add_u64 v[48:49], v[24:25], 0, v[48:49]
	v_lshl_add_u64 v[34:35], v[24:25], 0, v[34:35]
	v_lshlrev_b64 v[52:53], 12, v[4:5]
	v_or_b32_e32 v4, s36, v26
	v_mov_b32_e32 v37, v5
	v_mov_b32_e32 v39, v5
	s_add_i32 s40, s28, 20
	v_or_b32_e32 v36, s33, v3
	v_or_b32_e32 v38, s35, v3
	v_lshl_add_u64 v[32:33], v[24:25], 0, v[32:33]
	v_lshl_add_u64 v[50:51], v[24:25], 0, v[50:51]
	global_load_dword v21, v[48:49], off nt
	global_load_dword v23, v[32:33], off nt
	global_load_dword v64, v[50:51], off nt
	global_load_dword v65, v[34:35], off nt
	v_lshlrev_b64 v[34:35], 12, v[4:5]
	v_or_b32_e32 v4, s38, v26
	s_add_i32 s37, s27, 16
	s_add_i32 s39, s27, 20
	s_add_i32 s42, s28, 24
	v_lshlrev_b64 v[36:37], 12, v[36:37]
	v_lshlrev_b64 v[38:39], 12, v[38:39]
	v_lshl_add_u64 v[32:33], v[24:25], 0, v[52:53]
	v_lshl_add_u64 v[34:35], v[24:25], 0, v[34:35]
	v_lshlrev_b64 v[48:49], 12, v[4:5]
	v_or_b32_e32 v4, s40, v26
	v_mov_b32_e32 v41, v5
	v_mov_b32_e32 v43, v5
	s_add_i32 s41, s27, 24
	s_add_i32 s43, s27, 28
	s_add_i32 s44, s28, 28
	v_or_b32_e32 v40, s37, v3
	v_or_b32_e32 v42, s39, v3
	v_lshl_add_u64 v[36:37], v[24:25], 0, v[36:37]
	v_lshl_add_u64 v[38:39], v[24:25], 0, v[38:39]
	global_load_dword v66, v[32:33], off nt
	global_load_dword v67, v[36:37], off nt
	global_load_dword v68, v[34:35], off nt
	global_load_dword v69, v[38:39], off nt
	v_lshlrev_b64 v[34:35], 12, v[4:5]
	v_or_b32_e32 v4, s42, v26
	v_mov_b32_e32 v45, v5
	v_mov_b32_e32 v47, v5
	v_or_b32_e32 v44, s41, v3
	v_or_b32_e32 v46, s43, v3
	v_lshlrev_b64 v[40:41], 12, v[40:41]
	v_lshlrev_b64 v[42:43], 12, v[42:43]
	v_lshl_add_u64 v[32:33], v[24:25], 0, v[48:49]
	v_lshl_add_u64 v[34:35], v[24:25], 0, v[34:35]
	v_lshlrev_b64 v[36:37], 12, v[4:5]
	v_or_b32_e32 v4, s44, v26
	v_lshlrev_b64 v[44:45], 12, v[44:45]
	v_lshlrev_b64 v[46:47], 12, v[46:47]
	v_lshl_add_u64 v[40:41], v[24:25], 0, v[40:41]
	v_lshl_add_u64 v[42:43], v[24:25], 0, v[42:43]
	global_load_dword v70, v[32:33], off nt
	global_load_dword v71, v[40:41], off nt
	global_load_dword v72, v[34:35], off nt
	global_load_dword v73, v[42:43], off nt
	v_lshl_add_u64 v[32:33], v[24:25], 0, v[36:37]
	v_lshlrev_b64 v[34:35], 12, v[4:5]
	v_lshl_add_u64 v[44:45], v[24:25], 0, v[44:45]
	v_lshl_add_u64 v[46:47], v[24:25], 0, v[46:47]
	v_lshl_add_u64 v[34:35], v[24:25], 0, v[34:35]
	global_load_dword v4, v[32:33], off nt
	global_load_dword v74, v[44:45], off nt
	global_load_dword v75, v[34:35], off nt
	global_load_dword v76, v[46:47], off nt
	v_or_b32_e32 v34, s27, v1
	v_or_b32_e32 v32, s28, v2
	s_add_i32 s24, s24, 16
	s_add_i32 s23, s23, 16
	s_add_i32 s25, s25, -16
	v_mad_u64_u32 v[32:33], s[28:29], v32, s13, v[8:9]
	v_mad_u64_u32 v[34:35], s[28:29], v34, s13, v[8:9]
	v_or_b32_e32 v33, s30, v1
	v_or_b32_e32 v35, s31, v2
	v_or_b32_e32 v42, s33, v1
	v_or_b32_e32 v40, s34, v2
	v_or_b32_e32 v46, s35, v1
	v_or_b32_e32 v44, s36, v2
	v_or_b32_e32 v50, s37, v1
	v_or_b32_e32 v48, s38, v2
	v_or_b32_e32 v54, s39, v1
	v_or_b32_e32 v52, s40, v2
	v_or_b32_e32 v58, s41, v1
	v_or_b32_e32 v56, s42, v2
	v_or_b32_e32 v62, s43, v1
	v_or_b32_e32 v60, s44, v2
	s_cmp_lg_u32 s25, 0
	v_mad_u64_u32 v[36:37], s[28:29], v35, s13, v[8:9]
	v_mad_u64_u32 v[38:39], s[28:29], v33, s13, v[8:9]
	v_mad_u64_u32 v[40:41], s[28:29], v40, s13, v[8:9]
	v_mad_u64_u32 v[42:43], s[28:29], v42, s13, v[8:9]
	v_mad_u64_u32 v[44:45], s[28:29], v44, s13, v[8:9]
	v_mad_u64_u32 v[46:47], s[28:29], v46, s13, v[8:9]
	v_mad_u64_u32 v[48:49], s[28:29], v48, s13, v[8:9]
	v_mad_u64_u32 v[50:51], s[28:29], v50, s13, v[8:9]
	v_mad_u64_u32 v[52:53], s[28:29], v52, s13, v[8:9]
	v_mad_u64_u32 v[54:55], s[28:29], v54, s13, v[8:9]
	v_mad_u64_u32 v[56:57], s[28:29], v56, s13, v[8:9]
	v_mad_u64_u32 v[58:59], s[28:29], v58, s13, v[8:9]
	v_mad_u64_u32 v[60:61], s[28:29], v60, s13, v[8:9]
	v_mad_u64_u32 v[62:63], s[28:29], v62, s13, v[8:9]
	s_waitcnt vmcnt(15)
	ds_write_b32 v32, v21
	s_waitcnt vmcnt(14)
	ds_write_b32 v34, v23
	s_waitcnt vmcnt(13)
	ds_write_b32 v36, v64
	s_waitcnt vmcnt(12)
	ds_write_b32 v38, v65
	s_waitcnt vmcnt(11)
	ds_write_b32 v40, v66
	s_waitcnt vmcnt(10)
	ds_write_b32 v42, v67
	s_waitcnt vmcnt(9)
	ds_write_b32 v44, v68
	s_waitcnt vmcnt(8)
	ds_write_b32 v46, v69
	s_waitcnt vmcnt(7)
	ds_write_b32 v48, v70
	s_waitcnt vmcnt(6)
	ds_write_b32 v50, v71
	s_waitcnt vmcnt(5)
	ds_write_b32 v52, v72
	s_waitcnt vmcnt(4)
	ds_write_b32 v54, v73
	s_waitcnt vmcnt(3)
	ds_write_b32 v56, v4
	s_waitcnt vmcnt(2)
	ds_write_b32 v58, v74
	s_waitcnt vmcnt(1)
	ds_write_b32 v60, v75
	s_waitcnt vmcnt(0)
	ds_write_b32 v62, v76
	s_cbranch_scc1 .LBB0_29
; #define GAS __attribute__((address_space(1)))
; #define LAS __attribute__((address_space(3)))
; #define LDS_WAIT() asm volatile("s_waitcnt lgkmcnt(0)" ::: "memory")
; __device__ __forceinline__ unsigned pk2(float lo, float hi) { return f2bf(lo) | (f2bf(hi) << 16); }
; __device__ __forceinline__ void p0_transpose_item(const float* W, int ld, int K, int ncols, bf16* WT, LAS float* scr, int item, int lane) {
;     ...
;     LDS_WAIT(); asm volatile("" ::: "memory");
;     const int c = lane & 7;
; #pragma unroll
;     for (int j = 0; j < 4; ++j) { const int n = (lane >> 3) + 8 * j; const LAS float* s = scr + (8 * c) * 33 + n;
;         v4u o; o.x = pk2(s[0 * 33], s[1 * 33]); o.y = pk2(s[2 * 33], s[3 * 33]); o.z = pk2(s[4 * 33], s[5 * 33]); o.w = pk2(s[6 * 33], s[7 * 33]);
;         *(GAS v4u*)(WT + (size_t)(n0 + n) * K + k0 + 8 * c) = o; }
;     LDS_WAIT(); asm volatile("" ::: "memory");
	s_waitcnt lgkmcnt(0)
	ds_read2_b32 v[24:25], v28 offset1:8
	ds_read2_b32 v[38:39], v28 offset0:33 offset1:41
	ds_read2_b32 v[40:41], v28 offset0:66 offset1:74
	ds_read2_b32 v[42:43], v28 offset0:99 offset1:107
	ds_read2_b32 v[44:45], v28 offset0:132 offset1:140
	ds_read2_b32 v[46:47], v28 offset0:165 offset1:173
	s_waitcnt lgkmcnt(5)
	v_bfe_u32 v3, v24, 16, 1
	v_add3_u32 v3, v24, v3, s15
	s_waitcnt lgkmcnt(4)
	v_bfe_u32 v4, v38, 16, 1
	v_lshrrev_b32_e32 v3, 16, v3
	v_add3_u32 v4, v38, v4, s15
	v_and_or_b32 v32, v4, s16, v3
	s_waitcnt lgkmcnt(3)
	v_bfe_u32 v3, v40, 16, 1
	v_add3_u32 v3, v40, v3, s15
	s_waitcnt lgkmcnt(2)
	v_bfe_u32 v4, v42, 16, 1
	ds_read2_b32 v[48:49], v28 offset0:198 offset1:206
	v_lshrrev_b32_e32 v3, 16, v3
	v_add3_u32 v4, v42, v4, s15
	ds_read2_b32 v[50:51], v28 offset0:231 offset1:239
	v_and_or_b32 v33, v4, s16, v3
	s_waitcnt lgkmcnt(3)
	v_bfe_u32 v3, v44, 16, 1
	v_add3_u32 v3, v44, v3, s15
	s_waitcnt lgkmcnt(2)
	v_bfe_u32 v4, v46, 16, 1
	v_lshrrev_b32_e32 v3, 16, v3
	v_add3_u32 v4, v46, v4, s15
	v_and_or_b32 v34, v4, s16, v3
	s_waitcnt lgkmcnt(1)
	v_bfe_u32 v3, v48, 16, 1
	v_add3_u32 v3, v48, v3, s15
	s_waitcnt lgkmcnt(0)
	v_bfe_u32 v4, v50, 16, 1
	v_lshrrev_b32_e32 v3, 16, v3
	v_add3_u32 v4, v50, v4, s15
	s_lshl_b32 s6, s6, 1
	v_and_or_b32 v35, v4, s16, v3
	v_or_b32_e32 v3, s22, v27
	v_lshl_add_u64 v[36:37], v[12:13], 0, s[6:7]
	v_lshlrev_b32_e32 v4, 11, v3
	v_bfe_u32 v3, v25, 16, 1
	v_lshl_add_u64 v[52:53], v[36:37], 0, v[4:5]
	v_add3_u32 v3, v25, v3, s15
	v_bfe_u32 v4, v39, 16, 1
	v_lshrrev_b32_e32 v3, 16, v3
	v_add3_u32 v4, v39, v4, s15
	global_store_dwordx4 v[52:53], v[32:35], off
	ds_read2_b32 v[24:25], v28 offset0:16 offset1:24
	s_nop 0
	v_and_or_b32 v32, v4, s16, v3
	v_bfe_u32 v3, v41, 16, 1
	v_add3_u32 v3, v41, v3, s15
	v_bfe_u32 v4, v43, 16, 1
	v_lshrrev_b32_e32 v3, 16, v3
	v_add3_u32 v4, v43, v4, s15
	v_and_or_b32 v33, v4, s16, v3
	v_bfe_u32 v3, v45, 16, 1
	v_add3_u32 v3, v45, v3, s15
	v_bfe_u32 v4, v47, 16, 1
	v_lshrrev_b32_e32 v3, 16, v3
	v_add3_u32 v4, v47, v4, s15
	v_and_or_b32 v34, v4, s16, v3
	v_bfe_u32 v3, v49, 16, 1
	v_add3_u32 v3, v49, v3, s15
	v_bfe_u32 v4, v51, 16, 1
	v_lshrrev_b32_e32 v3, 16, v3
	v_add3_u32 v4, v51, v4, s15
	v_and_or_b32 v35, v4, s16, v3
	v_or_b32_e32 v3, s22, v29
	v_lshlrev_b32_e32 v4, 11, v3
	v_lshl_add_u64 v[38:39], v[36:37], 0, v[4:5]
	global_store_dwordx4 v[38:39], v[32:35], off
	ds_read2_b32 v[38:39], v28 offset0:49 offset1:57
	ds_read2_b32 v[40:41], v28 offset0:82 offset1:90
	ds_read2_b32 v[42:43], v28 offset0:115 offset1:123
	s_waitcnt lgkmcnt(3)
	v_bfe_u32 v3, v24, 16, 1
	v_add3_u32 v3, v24, v3, s15
	s_waitcnt lgkmcnt(2)
	v_bfe_u32 v4, v38, 16, 1
	ds_read2_b32 v[44:45], v28 offset0:148 offset1:156
	v_lshrrev_b32_e32 v3, 16, v3
	v_add3_u32 v4, v38, v4, s15
	ds_read2_b32 v[46:47], v28 offset0:181 offset1:189
	v_and_or_b32 v32, v4, s16, v3
	s_waitcnt lgkmcnt(3)
	v_bfe_u32 v3, v40, 16, 1
	v_add3_u32 v3, v40, v3, s15
	s_waitcnt lgkmcnt(2)
	v_bfe_u32 v4, v42, 16, 1
	ds_read2_b32 v[48:49], v28 offset0:214 offset1:222
	v_lshrrev_b32_e32 v3, 16, v3
	v_add3_u32 v4, v42, v4, s15
	ds_read2_b32 v[50:51], v28 offset0:247 offset1:255
	v_and_or_b32 v33, v4, s16, v3
	s_waitcnt lgkmcnt(3)
	v_bfe_u32 v3, v44, 16, 1
	v_add3_u32 v3, v44, v3, s15
	s_waitcnt lgkmcnt(2)
	v_bfe_u32 v4, v46, 16, 1
	v_lshrrev_b32_e32 v3, 16, v3
	v_add3_u32 v4, v46, v4, s15
	v_and_or_b32 v34, v4, s16, v3
	s_waitcnt lgkmcnt(1)
	v_bfe_u32 v3, v48, 16, 1
	v_add3_u32 v3, v48, v3, s15
	s_waitcnt lgkmcnt(0)
	v_bfe_u32 v4, v50, 16, 1
	v_lshrrev_b32_e32 v3, 16, v3
	v_add3_u32 v4, v50, v4, s15
	v_and_or_b32 v35, v4, s16, v3
	v_or_b32_e32 v3, s22, v30
	v_lshlrev_b32_e32 v4, 11, v3
	v_bfe_u32 v3, v25, 16, 1
	v_lshl_add_u64 v[52:53], v[36:37], 0, v[4:5]
	v_add3_u32 v3, v25, v3, s15
	v_bfe_u32 v4, v39, 16, 1
	v_lshrrev_b32_e32 v3, 16, v3
	v_add3_u32 v4, v39, v4, s15
	global_store_dwordx4 v[52:53], v[32:35], off
	s_nop 1
	v_and_or_b32 v32, v4, s16, v3
	v_bfe_u32 v3, v41, 16, 1
	v_add3_u32 v3, v41, v3, s15
	v_bfe_u32 v4, v43, 16, 1
	v_lshrrev_b32_e32 v3, 16, v3
	v_add3_u32 v4, v43, v4, s15
	v_and_or_b32 v33, v4, s16, v3
	v_bfe_u32 v3, v45, 16, 1
	v_add3_u32 v3, v45, v3, s15
	v_bfe_u32 v4, v47, 16, 1
	v_lshrrev_b32_e32 v3, 16, v3
	v_add3_u32 v4, v47, v4, s15
	v_and_or_b32 v34, v4, s16, v3
	v_bfe_u32 v3, v49, 16, 1
	v_add3_u32 v3, v49, v3, s15
	v_bfe_u32 v4, v51, 16, 1
	v_lshrrev_b32_e32 v3, 16, v3
	v_add3_u32 v4, v51, v4, s15
	v_and_or_b32 v35, v4, s16, v3
	v_or_b32_e32 v3, s22, v31
	v_lshlrev_b32_e32 v4, 11, v3
	v_lshl_add_u64 v[24:25], v[36:37], 0, v[4:5]
	global_store_dwordx4 v[24:25], v[32:35], off
	s_waitcnt lgkmcnt(0)

; #define LAS __attribute__((address_space(3)))
; __device__ __forceinline__ void p0_transpose_item(const float* W, int ld, int K, int ncols, bf16* WT, LAS float* scr, int item, int lane) {
;     const int nblk = ncols / 32, kb = item / nblk, nb = item % nblk, k0 = 64 * kb, n0 = 32 * nb;
; #pragma unroll 8
;     for (int i = 0; i < 32; ++i) { const int kk = 2 * i + (lane >> 5); scr[kk * 33 + (lane & 31)] = W[(size_t)(k0 + kk) * ld + n0 + (lane & 31)]; }
.LBB0_34:
	s_lshl_b32 s27, s23, 1
	s_lshl_b32 s28, s24, 1
	v_or_b32_e32 v4, s28, v26
	s_add_i32 s30, s27, 4
	s_add_i32 s31, s28, 4
	v_mov_b32_e32 v35, v5
	s_add_i32 s34, s28, 8
	v_lshlrev_b64 v[48:49], 12, v[4:5]
	v_or_b32_e32 v34, s30, v3
	v_or_b32_e32 v4, s31, v26
	v_mov_b32_e32 v33, v5
	v_or_b32_e32 v32, s27, v3
	s_add_i32 s36, s28, 12
	v_lshlrev_b64 v[34:35], 12, v[34:35]
	v_lshlrev_b64 v[50:51], 12, v[4:5]
	v_or_b32_e32 v4, s34, v26
	s_add_i32 s33, s27, 8
	s_add_i32 s35, s27, 12
	s_add_i32 s38, s28, 16
	v_lshlrev_b64 v[32:33], 12, v[32:33]
	v_lshl_add_u64 v[48:49], v[24:25], 0, v[48:49]
	v_lshl_add_u64 v[34:35], v[24:25], 0, v[34:35]
	v_lshlrev_b64 v[52:53], 12, v[4:5]
	v_or_b32_e32 v4, s36, v26
	v_mov_b32_e32 v37, v5
	v_mov_b32_e32 v39, v5
	s_add_i32 s40, s28, 20
	v_or_b32_e32 v36, s33, v3
	v_or_b32_e32 v38, s35, v3
	v_lshl_add_u64 v[32:33], v[24:25], 0, v[32:33]
	v_lshl_add_u64 v[50:51], v[24:25], 0, v[50:51]
	global_load_dword v21, v[48:49], off nt
	global_load_dword v23, v[32:33], off nt
	global_load_dword v64, v[50:51], off nt
	global_load_dword v65, v[34:35], off nt
	v_lshlrev_b64 v[34:35], 12, v[4:5]
	v_or_b32_e32 v4, s38, v26
	s_add_i32 s37, s27, 16
	s_add_i32 s39, s27, 20
	s_add_i32 s42, s28, 24
	v_lshlrev_b64 v[36:37], 12, v[36:37]
	v_lshlrev_b64 v[38:39], 12, v[38:39]
	v_lshl_add_u64 v[32:33], v[24:25], 0, v[52:53]
	v_lshl_add_u64 v[34:35], v[24:25], 0, v[34:35]
	v_lshlrev_b64 v[48:49], 12, v[4:5]
	v_or_b32_e32 v4, s40, v26
	v_mov_b32_e32 v41, v5
	v_mov_b32_e32 v43, v5
	s_add_i32 s41, s27, 24
	s_add_i32 s43, s27, 28
	s_add_i32 s44, s28, 28
	v_or_b32_e32 v40, s37, v3
	v_or_b32_e32 v42, s39, v3
	v_lshl_add_u64 v[36:37], v[24:25], 0, v[36:37]
	v_lshl_add_u64 v[38:39], v[24:25], 0, v[38:39]
	global_load_dword v66, v[32:33], off nt
	global_load_dword v67, v[36:37], off nt
	global_load_dword v68, v[34:35], off nt
	global_load_dword v69, v[38:39], off nt
	v_lshlrev_b64 v[34:35], 12, v[4:5]
	v_or_b32_e32 v4, s42, v26
	v_mov_b32_e32 v45, v5
	v_mov_b32_e32 v47, v5
	v_or_b32_e32 v44, s41, v3
	v_or_b32_e32 v46, s43, v3
	v_lshlrev_b64 v[40:41], 12, v[40:41]
	v_lshlrev_b64 v[42:43], 12, v[42:43]
	v_lshl_add_u64 v[32:33], v[24:25], 0, v[48:49]
	v_lshl_add_u64 v[34:35], v[24:25], 0, v[34:35]
	v_lshlrev_b64 v[36:37], 12, v[4:5]
	v_or_b32_e32 v4, s44, v26
	v_lshlrev_b64 v[44:45], 12, v[44:45]
	v_lshlrev_b64 v[46:47], 12, v[46:47]
	v_lshl_add_u64 v[40:41], v[24:25], 0, v[40:41]
	v_lshl_add_u64 v[42:43], v[24:25], 0, v[42:43]
	global_load_dword v70, v[32:33], off nt
	global_load_dword v71, v[40:41], off nt
	global_load_dword v72, v[34:35], off nt
	global_load_dword v73, v[42:43], off nt
	v_lshl_add_u64 v[32:33], v[24:25], 0, v[36:37]
	v_lshlrev_b64 v[34:35], 12, v[4:5]
	v_lshl_add_u64 v[44:45], v[24:25], 0, v[44:45]
	v_lshl_add_u64 v[46:47], v[24:25], 0, v[46:47]
	v_lshl_add_u64 v[34:35], v[24:25], 0, v[34:35]
	global_load_dword v4, v[32:33], off nt
	global_load_dword v74, v[44:45], off nt
	global_load_dword v75, v[34:35], off nt
	global_load_dword v76, v[46:47], off nt
	v_or_b32_e32 v34, s27, v1
	v_or_b32_e32 v32, s28, v2
	s_add_i32 s24, s24, 16
	s_add_i32 s23, s23, 16
	s_add_i32 s25, s25, -16
	v_mad_u64_u32 v[32:33], s[28:29], v32, s13, v[8:9]
	v_mad_u64_u32 v[34:35], s[28:29], v34, s13, v[8:9]
	v_or_b32_e32 v33, s30, v1
	v_or_b32_e32 v35, s31, v2
	v_or_b32_e32 v42, s33, v1
	v_or_b32_e32 v40, s34, v2
	v_or_b32_e32 v46, s35, v1
	v_or_b32_e32 v44, s36, v2
	v_or_b32_e32 v50, s37, v1
	v_or_b32_e32 v48, s38, v2
	v_or_b32_e32 v54, s39, v1
	v_or_b32_e32 v52, s40, v2
	v_or_b32_e32 v58, s41, v1
	v_or_b32_e32 v56, s42, v2
	v_or_b32_e32 v62, s43, v1
	v_or_b32_e32 v60, s44, v2
	s_cmp_lg_u32 s25, 0
	v_mad_u64_u32 v[36:37], s[28:29], v35, s13, v[8:9]
	v_mad_u64_u32 v[38:39], s[28:29], v33, s13, v[8:9]
	v_mad_u64_u32 v[40:41], s[28:29], v40, s13, v[8:9]
	v_mad_u64_u32 v[42:43], s[28:29], v42, s13, v[8:9]
	v_mad_u64_u32 v[44:45], s[28:29], v44, s13, v[8:9]
	v_mad_u64_u32 v[46:47], s[28:29], v46, s13, v[8:9]
	v_mad_u64_u32 v[48:49], s[28:29], v48, s13, v[8:9]
	v_mad_u64_u32 v[50:51], s[28:29], v50, s13, v[8:9]
	v_mad_u64_u32 v[52:53], s[28:29], v52, s13, v[8:9]
	v_mad_u64_u32 v[54:55], s[28:29], v54, s13, v[8:9]
	v_mad_u64_u32 v[56:57], s[28:29], v56, s13, v[8:9]
	v_mad_u64_u32 v[58:59], s[28:29], v58, s13, v[8:9]
	v_mad_u64_u32 v[60:61], s[28:29], v60, s13, v[8:9]
	v_mad_u64_u32 v[62:63], s[28:29], v62, s13, v[8:9]
	s_waitcnt vmcnt(15)
	ds_write_b32 v32, v21
	s_waitcnt vmcnt(14)
	ds_write_b32 v34, v23
	s_waitcnt vmcnt(13)
	ds_write_b32 v36, v64
	s_waitcnt vmcnt(12)
	ds_write_b32 v38, v65
	s_waitcnt vmcnt(11)
	ds_write_b32 v40, v66
	s_waitcnt vmcnt(10)
	ds_write_b32 v42, v67
	s_waitcnt vmcnt(9)
	ds_write_b32 v44, v68
	s_waitcnt vmcnt(8)
	ds_write_b32 v46, v69
	s_waitcnt vmcnt(7)
	ds_write_b32 v48, v70
	s_waitcnt vmcnt(6)
	ds_write_b32 v50, v71
	s_waitcnt vmcnt(5)
	ds_write_b32 v52, v72
	s_waitcnt vmcnt(4)
	ds_write_b32 v54, v73
	s_waitcnt vmcnt(3)
	ds_write_b32 v56, v4
	s_waitcnt vmcnt(2)
	ds_write_b32 v58, v74
	s_waitcnt vmcnt(1)
	ds_write_b32 v60, v75
	s_waitcnt vmcnt(0)
	ds_write_b32 v62, v76
	s_cbranch_scc1 .LBB0_34
; #define GAS __attribute__((address_space(1)))
; #define LAS __attribute__((address_space(3)))
; #define LDS_WAIT() asm volatile("s_waitcnt lgkmcnt(0)" ::: "memory")
; __device__ __forceinline__ unsigned pk2(float lo, float hi) { return f2bf(lo) | (f2bf(hi) << 16); }
; __device__ __forceinline__ void p0_transpose_item(const float* W, int ld, int K, int ncols, bf16* WT, LAS float* scr, int item, int lane) {
;     ...
;     LDS_WAIT(); asm volatile("" ::: "memory");
;     const int c = lane & 7;
; #pragma unroll
;     for (int j = 0; j < 4; ++j) { const int n = (lane >> 3) + 8 * j; const LAS float* s = scr + (8 * c) * 33 + n;
;         v4u o; o.x = pk2(s[0 * 33], s[1 * 33]); o.y = pk2(s[2 * 33], s[3 * 33]); o.z = pk2(s[4 * 33], s[5 * 33]); o.w = pk2(s[6 * 33], s[7 * 33]);
;         *(GAS v4u*)(WT + (size_t)(n0 + n) * K + k0 + 8 * c) = o; }
;     LDS_WAIT(); asm volatile("" ::: "memory");
	s_waitcnt lgkmcnt(0)
	ds_read2_b32 v[24:25], v28 offset1:8
	ds_read2_b32 v[38:39], v28 offset0:33 offset1:41
	ds_read2_b32 v[40:41], v28 offset0:66 offset1:74
	ds_read2_b32 v[42:43], v28 offset0:99 offset1:107
	ds_read2_b32 v[44:45], v28 offset0:132 offset1:140
	ds_read2_b32 v[46:47], v28 offset0:165 offset1:173
	s_waitcnt lgkmcnt(5)
	v_bfe_u32 v3, v24, 16, 1
	v_add3_u32 v3, v24, v3, s15
	s_waitcnt lgkmcnt(4)
	v_bfe_u32 v4, v38, 16, 1
	v_lshrrev_b32_e32 v3, 16, v3
	v_add3_u32 v4, v38, v4, s15
	v_and_or_b32 v32, v4, s16, v3
	s_waitcnt lgkmcnt(3)
	v_bfe_u32 v3, v40, 16, 1
	v_add3_u32 v3, v40, v3, s15
	s_waitcnt lgkmcnt(2)
	v_bfe_u32 v4, v42, 16, 1
	ds_read2_b32 v[48:49], v28 offset0:198 offset1:206
	v_lshrrev_b32_e32 v3, 16, v3
	v_add3_u32 v4, v42, v4, s15
	ds_read2_b32 v[50:51], v28 offset0:231 offset1:239
	v_and_or_b32 v33, v4, s16, v3
	s_waitcnt lgkmcnt(3)
	v_bfe_u32 v3, v44, 16, 1
	v_add3_u32 v3, v44, v3, s15
	s_waitcnt lgkmcnt(2)
	v_bfe_u32 v4, v46, 16, 1
	v_lshrrev_b32_e32 v3, 16, v3
	v_add3_u32 v4, v46, v4, s15
	v_and_or_b32 v34, v4, s16, v3
	s_waitcnt lgkmcnt(1)
	v_bfe_u32 v3, v48, 16, 1
	v_add3_u32 v3, v48, v3, s15
	s_waitcnt lgkmcnt(0)
	v_bfe_u32 v4, v50, 16, 1
	v_lshrrev_b32_e32 v3, 16, v3
	v_add3_u32 v4, v50, v4, s15
	s_lshl_b32 s6, s6, 1
	v_and_or_b32 v35, v4, s16, v3
	v_or_b32_e32 v3, s22, v27
	v_lshl_add_u64 v[36:37], v[14:15], 0, s[6:7]
	v_lshlrev_b32_e32 v4, 11, v3
	v_bfe_u32 v3, v25, 16, 1
	v_lshl_add_u64 v[52:53], v[36:37], 0, v[4:5]
	v_add3_u32 v3, v25, v3, s15
	v_bfe_u32 v4, v39, 16, 1
	v_lshrrev_b32_e32 v3, 16, v3
	v_add3_u32 v4, v39, v4, s15
	global_store_dwordx4 v[52:53], v[32:35], off
	ds_read2_b32 v[24:25], v28 offset0:16 offset1:24
	s_nop 0
	v_and_or_b32 v32, v4, s16, v3
	v_bfe_u32 v3, v41, 16, 1
	v_add3_u32 v3, v41, v3, s15
	v_bfe_u32 v4, v43, 16, 1
	v_lshrrev_b32_e32 v3, 16, v3
	v_add3_u32 v4, v43, v4, s15
	v_and_or_b32 v33, v4, s16, v3
	v_bfe_u32 v3, v45, 16, 1
	v_add3_u32 v3, v45, v3, s15
	v_bfe_u32 v4, v47, 16, 1
	v_lshrrev_b32_e32 v3, 16, v3
	v_add3_u32 v4, v47, v4, s15
	v_and_or_b32 v34, v4, s16, v3
	v_bfe_u32 v3, v49, 16, 1
	v_add3_u32 v3, v49, v3, s15
	v_bfe_u32 v4, v51, 16, 1
	v_lshrrev_b32_e32 v3, 16, v3
	v_add3_u32 v4, v51, v4, s15
	v_and_or_b32 v35, v4, s16, v3
	v_or_b32_e32 v3, s22, v29
	v_lshlrev_b32_e32 v4, 11, v3
	v_lshl_add_u64 v[38:39], v[36:37], 0, v[4:5]
	global_store_dwordx4 v[38:39], v[32:35], off
	ds_read2_b32 v[38:39], v28 offset0:49 offset1:57
	ds_read2_b32 v[40:41], v28 offset0:82 offset1:90
	ds_read2_b32 v[42:43], v28 offset0:115 offset1:123
	s_waitcnt lgkmcnt(3)
	v_bfe_u32 v3, v24, 16, 1
	v_add3_u32 v3, v24, v3, s15
	s_waitcnt lgkmcnt(2)
	v_bfe_u32 v4, v38, 16, 1
	ds_read2_b32 v[44:45], v28 offset0:148 offset1:156
	v_lshrrev_b32_e32 v3, 16, v3
	v_add3_u32 v4, v38, v4, s15
	ds_read2_b32 v[46:47], v28 offset0:181 offset1:189
	v_and_or_b32 v32, v4, s16, v3
	s_waitcnt lgkmcnt(3)
	v_bfe_u32 v3, v40, 16, 1
	v_add3_u32 v3, v40, v3, s15
	s_waitcnt lgkmcnt(2)
	v_bfe_u32 v4, v42, 16, 1
	ds_read2_b32 v[48:49], v28 offset0:214 offset1:222
	v_lshrrev_b32_e32 v3, 16, v3
	v_add3_u32 v4, v42, v4, s15
	ds_read2_b32 v[50:51], v28 offset0:247 offset1:255
	v_and_or_b32 v33, v4, s16, v3
	s_waitcnt lgkmcnt(3)
	v_bfe_u32 v3, v44, 16, 1
	v_add3_u32 v3, v44, v3, s15
	s_waitcnt lgkmcnt(2)
	v_bfe_u32 v4, v46, 16, 1
	v_lshrrev_b32_e32 v3, 16, v3
	v_add3_u32 v4, v46, v4, s15
	v_and_or_b32 v34, v4, s16, v3
	s_waitcnt lgkmcnt(1)
	v_bfe_u32 v3, v48, 16, 1
	v_add3_u32 v3, v48, v3, s15
	s_waitcnt lgkmcnt(0)
	v_bfe_u32 v4, v50, 16, 1
	v_lshrrev_b32_e32 v3, 16, v3
	v_add3_u32 v4, v50, v4, s15
	v_and_or_b32 v35, v4, s16, v3
	v_or_b32_e32 v3, s22, v30
	v_lshlrev_b32_e32 v4, 11, v3
	v_bfe_u32 v3, v25, 16, 1
	v_lshl_add_u64 v[52:53], v[36:37], 0, v[4:5]
	v_add3_u32 v3, v25, v3, s15
	v_bfe_u32 v4, v39, 16, 1
	v_lshrrev_b32_e32 v3, 16, v3
	v_add3_u32 v4, v39, v4, s15
	global_store_dwordx4 v[52:53], v[32:35], off
	s_nop 1
	v_and_or_b32 v32, v4, s16, v3
	v_bfe_u32 v3, v41, 16, 1
	v_add3_u32 v3, v41, v3, s15
	v_bfe_u32 v4, v43, 16, 1
	v_lshrrev_b32_e32 v3, 16, v3
	v_add3_u32 v4, v43, v4, s15
	v_and_or_b32 v33, v4, s16, v3
	v_bfe_u32 v3, v45, 16, 1
	v_add3_u32 v3, v45, v3, s15
	v_bfe_u32 v4, v47, 16, 1
	v_lshrrev_b32_e32 v3, 16, v3
	v_add3_u32 v4, v47, v4, s15
	v_and_or_b32 v34, v4, s16, v3
	v_bfe_u32 v3, v49, 16, 1
	v_add3_u32 v3, v49, v3, s15
	v_bfe_u32 v4, v51, 16, 1
	v_lshrrev_b32_e32 v3, 16, v3
	v_add3_u32 v4, v51, v4, s15
	v_and_or_b32 v35, v4, s16, v3
	v_or_b32_e32 v3, s22, v31
	v_lshlrev_b32_e32 v4, 11, v3
	v_lshl_add_u64 v[24:25], v[36:37], 0, v[4:5]
	global_store_dwordx4 v[24:25], v[32:35], off
	s_waitcnt lgkmcnt(0)

; #define LAS __attribute__((address_space(3)))
; __device__ __forceinline__ void p0_transpose_item(const float* W, int ld, int K, int ncols, bf16* WT, LAS float* scr, int item, int lane) {
;     const int nblk = ncols / 32, kb = item / nblk, nb = item % nblk, k0 = 64 * kb, n0 = 32 * nb;
; #pragma unroll 8
;     for (int i = 0; i < 32; ++i) { const int kk = 2 * i + (lane >> 5); scr[kk * 33 + (lane & 31)] = W[(size_t)(k0 + kk) * ld + n0 + (lane & 31)]; }
.LBB0_39:
	s_lshl_b32 s27, s23, 1
	s_lshl_b32 s30, s24, 1
	v_or_b32_e32 v21, s27, v3
	v_or_b32_e32 v23, s30, v4
	s_add_i32 s31, s27, 4
	s_add_i32 s33, s30, 4
	s_add_i32 s34, s27, 8
	s_add_i32 s35, s30, 8
	s_add_i32 s36, s27, 12
	s_add_i32 s37, s30, 12
	s_add_i32 s38, s27, 16
	s_add_i32 s39, s30, 16
	s_add_i32 s40, s27, 20
	s_add_i32 s41, s30, 20
	s_add_i32 s42, s27, 24
	s_add_i32 s43, s30, 24
	s_add_i32 s44, s27, 28
	s_add_i32 s45, s30, 28
	v_mad_u64_u32 v[32:33], s[28:29], v23, s17, v[24:25]
	v_mad_u64_u32 v[34:35], s[28:29], v21, s17, v[24:25]
	v_or_b32_e32 v21, s31, v3
	v_or_b32_e32 v23, s33, v4
	v_or_b32_e32 v26, s34, v3
	v_or_b32_e32 v40, s35, v4
	v_or_b32_e32 v46, s36, v3
	v_or_b32_e32 v44, s37, v4
	v_or_b32_e32 v50, s38, v3
	v_or_b32_e32 v48, s39, v4
	v_or_b32_e32 v54, s40, v3
	v_or_b32_e32 v52, s41, v4
	v_or_b32_e32 v58, s42, v3
	v_or_b32_e32 v56, s43, v4
	v_or_b32_e32 v62, s44, v3
	v_or_b32_e32 v60, s45, v4
	v_mad_u64_u32 v[36:37], s[28:29], v23, s17, v[24:25]
	v_mad_u64_u32 v[38:39], s[28:29], v21, s17, v[24:25]
	v_mad_u64_u32 v[40:41], s[28:29], v40, s17, v[24:25]
	v_mad_u64_u32 v[42:43], s[28:29], v26, s17, v[24:25]
	v_mad_u64_u32 v[44:45], s[28:29], v44, s17, v[24:25]
	v_mad_u64_u32 v[46:47], s[28:29], v46, s17, v[24:25]
	v_mad_u64_u32 v[48:49], s[28:29], v48, s17, v[24:25]
	v_mad_u64_u32 v[50:51], s[28:29], v50, s17, v[24:25]
	v_mad_u64_u32 v[52:53], s[28:29], v52, s17, v[24:25]
	v_mad_u64_u32 v[54:55], s[28:29], v54, s17, v[24:25]
	v_mad_u64_u32 v[56:57], s[28:29], v56, s17, v[24:25]
	v_mad_u64_u32 v[58:59], s[28:29], v58, s17, v[24:25]
	v_mad_u64_u32 v[60:61], s[28:29], v60, s17, v[24:25]
	v_mad_u64_u32 v[62:63], s[28:29], v62, s17, v[24:25]
	global_load_dword v21, v[32:33], off nt
	global_load_dword v23, v[34:35], off nt
	global_load_dword v26, v[36:37], off nt
	global_load_dword v64, v[38:39], off nt
	global_load_dword v65, v[40:41], off nt
	global_load_dword v66, v[42:43], off nt
	global_load_dword v67, v[44:45], off nt
	global_load_dword v68, v[46:47], off nt
	global_load_dword v69, v[48:49], off nt
	global_load_dword v70, v[50:51], off nt
	global_load_dword v71, v[52:53], off nt
	global_load_dword v72, v[54:55], off nt
	global_load_dword v73, v[56:57], off nt
	global_load_dword v74, v[58:59], off nt
	global_load_dword v75, v[60:61], off nt
	global_load_dword v76, v[62:63], off nt
	v_or_b32_e32 v34, s27, v1
	v_or_b32_e32 v32, s30, v2
	s_add_i32 s24, s24, 16
	s_add_i32 s23, s23, 16
	s_add_i32 s25, s25, -16
	v_mad_u64_u32 v[32:33], s[28:29], v32, s13, v[8:9]
	v_mad_u64_u32 v[34:35], s[28:29], v34, s13, v[8:9]
	v_or_b32_e32 v33, s31, v1
	v_or_b32_e32 v35, s33, v2
	v_or_b32_e32 v42, s34, v1
	v_or_b32_e32 v40, s35, v2
	v_or_b32_e32 v46, s36, v1
	v_or_b32_e32 v44, s37, v2
	v_or_b32_e32 v50, s38, v1
	v_or_b32_e32 v48, s39, v2
	v_or_b32_e32 v54, s40, v1
	v_or_b32_e32 v52, s41, v2
	v_or_b32_e32 v58, s42, v1
	v_or_b32_e32 v56, s43, v2
	v_or_b32_e32 v62, s44, v1
	v_or_b32_e32 v60, s45, v2
	s_cmp_lg_u32 s25, 0
	v_mad_u64_u32 v[36:37], s[28:29], v35, s13, v[8:9]
	v_mad_u64_u32 v[38:39], s[28:29], v33, s13, v[8:9]
	v_mad_u64_u32 v[40:41], s[28:29], v40, s13, v[8:9]
	v_mad_u64_u32 v[42:43], s[28:29], v42, s13, v[8:9]
	v_mad_u64_u32 v[44:45], s[28:29], v44, s13, v[8:9]
	v_mad_u64_u32 v[46:47], s[28:29], v46, s13, v[8:9]
	v_mad_u64_u32 v[48:49], s[28:29], v48, s13, v[8:9]
	v_mad_u64_u32 v[50:51], s[28:29], v50, s13, v[8:9]
	v_mad_u64_u32 v[52:53], s[28:29], v52, s13, v[8:9]
	v_mad_u64_u32 v[54:55], s[28:29], v54, s13, v[8:9]
	v_mad_u64_u32 v[56:57], s[28:29], v56, s13, v[8:9]
	v_mad_u64_u32 v[58:59], s[28:29], v58, s13, v[8:9]
	v_mad_u64_u32 v[60:61], s[28:29], v60, s13, v[8:9]
	v_mad_u64_u32 v[62:63], s[28:29], v62, s13, v[8:9]
	s_waitcnt vmcnt(15)
	ds_write_b32 v32, v21
	s_waitcnt vmcnt(14)
	ds_write_b32 v34, v23
	s_waitcnt vmcnt(13)
	ds_write_b32 v36, v26
	s_waitcnt vmcnt(12)
	ds_write_b32 v38, v64
	s_waitcnt vmcnt(11)
	ds_write_b32 v40, v65
	s_waitcnt vmcnt(10)
	ds_write_b32 v42, v66
	s_waitcnt vmcnt(9)
	ds_write_b32 v44, v67
	s_waitcnt vmcnt(8)
	ds_write_b32 v46, v68
	s_waitcnt vmcnt(7)
	ds_write_b32 v48, v69
	s_waitcnt vmcnt(6)
	ds_write_b32 v50, v70
	s_waitcnt vmcnt(5)
	ds_write_b32 v52, v71
	s_waitcnt vmcnt(4)
	ds_write_b32 v54, v72
	s_waitcnt vmcnt(3)
	ds_write_b32 v56, v73
	s_waitcnt vmcnt(2)
	ds_write_b32 v58, v74
	s_waitcnt vmcnt(1)
	ds_write_b32 v60, v75
	s_waitcnt vmcnt(0)
	ds_write_b32 v62, v76
	s_cbranch_scc1 .LBB0_39
; #define GAS __attribute__((address_space(1)))
; #define LAS __attribute__((address_space(3)))
; #define LDS_WAIT() asm volatile("s_waitcnt lgkmcnt(0)" ::: "memory")
; __device__ __forceinline__ unsigned pk2(float lo, float hi) { return f2bf(lo) | (f2bf(hi) << 16); }
; __device__ __forceinline__ void p0_transpose_item(const float* W, int ld, int K, int ncols, bf16* WT, LAS float* scr, int item, int lane) {
;     ...
;     LDS_WAIT(); asm volatile("" ::: "memory");
;     const int c = lane & 7;
; #pragma unroll
;     for (int j = 0; j < 4; ++j) { const int n = (lane >> 3) + 8 * j; const LAS float* s = scr + (8 * c) * 33 + n;
;         v4u o; o.x = pk2(s[0 * 33], s[1 * 33]); o.y = pk2(s[2 * 33], s[3 * 33]); o.z = pk2(s[4 * 33], s[5 * 33]); o.w = pk2(s[6 * 33], s[7 * 33]);
;         *(GAS v4u*)(WT + (size_t)(n0 + n) * K + k0 + 8 * c) = o; }
;     LDS_WAIT(); asm volatile("" ::: "memory");
	s_waitcnt lgkmcnt(0)
	ds_read2_b32 v[24:25], v28 offset1:8
	ds_read2_b32 v[38:39], v28 offset0:33 offset1:41
	ds_read2_b32 v[40:41], v28 offset0:66 offset1:74
	ds_read2_b32 v[42:43], v28 offset0:99 offset1:107
	ds_read2_b32 v[44:45], v28 offset0:132 offset1:140
	s_waitcnt lgkmcnt(4)
	v_bfe_u32 v3, v24, 16, 1
	v_add3_u32 v3, v24, v3, s15
	s_waitcnt lgkmcnt(3)
	v_bfe_u32 v4, v38, 16, 1
	v_lshrrev_b32_e32 v3, 16, v3
	v_add3_u32 v4, v38, v4, s15
	ds_read2_b32 v[46:47], v28 offset0:165 offset1:173
	v_and_or_b32 v32, v4, s16, v3
	s_waitcnt lgkmcnt(3)
	v_bfe_u32 v3, v40, 16, 1
	v_add3_u32 v3, v40, v3, s15
	s_waitcnt lgkmcnt(2)
	v_bfe_u32 v4, v42, 16, 1
	ds_read2_b32 v[48:49], v28 offset0:198 offset1:206
	v_lshrrev_b32_e32 v3, 16, v3
	v_add3_u32 v4, v42, v4, s15
	ds_read2_b32 v[50:51], v28 offset0:231 offset1:239
	v_and_or_b32 v33, v4, s16, v3
	s_waitcnt lgkmcnt(3)
	v_bfe_u32 v3, v44, 16, 1
	v_add3_u32 v3, v44, v3, s15
	s_waitcnt lgkmcnt(2)
	v_bfe_u32 v4, v46, 16, 1
	v_lshrrev_b32_e32 v3, 16, v3
	v_add3_u32 v4, v46, v4, s15
	v_and_or_b32 v34, v4, s16, v3
	s_waitcnt lgkmcnt(1)
	v_bfe_u32 v3, v48, 16, 1
	v_add3_u32 v3, v48, v3, s15
	s_waitcnt lgkmcnt(0)
	v_bfe_u32 v4, v50, 16, 1
	s_and_b32 s22, 0xffff, s22
	s_and_b32 s6, 0xffff, s6
	v_lshrrev_b32_e32 v3, 16, v3
	v_add3_u32 v4, v50, v4, s15
	s_lshl_b32 s6, s6, 1
	v_and_or_b32 v35, v4, s16, v3
	v_or_b32_e32 v3, s22, v27
	v_lshl_add_u64 v[36:37], v[16:17], 0, s[6:7]
	v_lshlrev_b32_e32 v4, 11, v3
	v_bfe_u32 v3, v25, 16, 1
	v_lshl_add_u64 v[52:53], v[36:37], 0, v[4:5]
	v_add3_u32 v3, v25, v3, s15
	v_bfe_u32 v4, v39, 16, 1
	v_lshrrev_b32_e32 v3, 16, v3
	v_add3_u32 v4, v39, v4, s15
	global_store_dwordx4 v[52:53], v[32:35], off
	ds_read2_b32 v[24:25], v28 offset0:16 offset1:24
	s_nop 0
	v_and_or_b32 v32, v4, s16, v3
	v_bfe_u32 v3, v41, 16, 1
	v_add3_u32 v3, v41, v3, s15
	v_bfe_u32 v4, v43, 16, 1
	v_lshrrev_b32_e32 v3, 16, v3
	v_add3_u32 v4, v43, v4, s15
	v_and_or_b32 v33, v4, s16, v3
	v_bfe_u32 v3, v45, 16, 1
	v_add3_u32 v3, v45, v3, s15
	v_bfe_u32 v4, v47, 16, 1
	v_lshrrev_b32_e32 v3, 16, v3
	v_add3_u32 v4, v47, v4, s15
	v_and_or_b32 v34, v4, s16, v3
	v_bfe_u32 v3, v49, 16, 1
	v_add3_u32 v3, v49, v3, s15
	v_bfe_u32 v4, v51, 16, 1
	v_lshrrev_b32_e32 v3, 16, v3
	v_add3_u32 v4, v51, v4, s15
	v_and_or_b32 v35, v4, s16, v3
	v_or_b32_e32 v3, s22, v29
	v_lshlrev_b32_e32 v4, 11, v3
	v_lshl_add_u64 v[38:39], v[36:37], 0, v[4:5]
	global_store_dwordx4 v[38:39], v[32:35], off
	ds_read2_b32 v[38:39], v28 offset0:49 offset1:57
	ds_read2_b32 v[40:41], v28 offset0:82 offset1:90
	ds_read2_b32 v[42:43], v28 offset0:115 offset1:123
	s_waitcnt lgkmcnt(3)
	v_bfe_u32 v3, v24, 16, 1
	v_add3_u32 v3, v24, v3, s15
	s_waitcnt lgkmcnt(2)
	v_bfe_u32 v4, v38, 16, 1
	ds_read2_b32 v[44:45], v28 offset0:148 offset1:156
	v_lshrrev_b32_e32 v3, 16, v3
	v_add3_u32 v4, v38, v4, s15
	ds_read2_b32 v[46:47], v28 offset0:181 offset1:189
	v_and_or_b32 v32, v4, s16, v3
	s_waitcnt lgkmcnt(3)
	v_bfe_u32 v3, v40, 16, 1
	v_add3_u32 v3, v40, v3, s15
	s_waitcnt lgkmcnt(2)
	v_bfe_u32 v4, v42, 16, 1
	ds_read2_b32 v[48:49], v28 offset0:214 offset1:222
	v_lshrrev_b32_e32 v3, 16, v3
	v_add3_u32 v4, v42, v4, s15
	ds_read2_b32 v[50:51], v28 offset0:247 offset1:255
	v_and_or_b32 v33, v4, s16, v3
	s_waitcnt lgkmcnt(3)
	v_bfe_u32 v3, v44, 16, 1
	v_add3_u32 v3, v44, v3, s15
	s_waitcnt lgkmcnt(2)
	v_bfe_u32 v4, v46, 16, 1
	v_lshrrev_b32_e32 v3, 16, v3
	v_add3_u32 v4, v46, v4, s15
	v_and_or_b32 v34, v4, s16, v3
	s_waitcnt lgkmcnt(1)
	v_bfe_u32 v3, v48, 16, 1
	v_add3_u32 v3, v48, v3, s15
	s_waitcnt lgkmcnt(0)
	v_bfe_u32 v4, v50, 16, 1
	v_lshrrev_b32_e32 v3, 16, v3
	v_add3_u32 v4, v50, v4, s15
	v_and_or_b32 v35, v4, s16, v3
	v_or_b32_e32 v3, s22, v30
	v_lshlrev_b32_e32 v4, 11, v3
	v_bfe_u32 v3, v25, 16, 1
	v_lshl_add_u64 v[52:53], v[36:37], 0, v[4:5]
	v_add3_u32 v3, v25, v3, s15
	v_bfe_u32 v4, v39, 16, 1
	v_lshrrev_b32_e32 v3, 16, v3
	v_add3_u32 v4, v39, v4, s15
	global_store_dwordx4 v[52:53], v[32:35], off
	s_nop 1
	v_and_or_b32 v32, v4, s16, v3
	v_bfe_u32 v3, v41, 16, 1
	v_add3_u32 v3, v41, v3, s15
	v_bfe_u32 v4, v43, 16, 1
	v_lshrrev_b32_e32 v3, 16, v3
	v_add3_u32 v4, v43, v4, s15
	v_and_or_b32 v33, v4, s16, v3
	v_bfe_u32 v3, v45, 16, 1
	v_add3_u32 v3, v45, v3, s15
	v_bfe_u32 v4, v47, 16, 1
	v_lshrrev_b32_e32 v3, 16, v3
	v_add3_u32 v4, v47, v4, s15
	v_and_or_b32 v34, v4, s16, v3
	v_bfe_u32 v3, v49, 16, 1
	v_add3_u32 v3, v49, v3, s15
	v_bfe_u32 v4, v51, 16, 1
	v_lshrrev_b32_e32 v3, 16, v3
	v_add3_u32 v4, v51, v4, s15
	v_and_or_b32 v35, v4, s16, v3
	v_or_b32_e32 v3, s22, v31
	v_lshlrev_b32_e32 v4, 11, v3
	v_lshl_add_u64 v[24:25], v[36:37], 0, v[4:5]
	global_store_dwordx4 v[24:25], v[32:35], off
	s_waitcnt lgkmcnt(0)

; #define LAS __attribute__((address_space(3)))
; __device__ __forceinline__ void p0_transpose_item(const float* W, int ld, int K, int ncols, bf16* WT, LAS float* scr, int item, int lane) {
;     const int nblk = ncols / 32, kb = item / nblk, nb = item % nblk, k0 = 64 * kb, n0 = 32 * nb;
; #pragma unroll 8
;     for (int i = 0; i < 32; ++i) { const int kk = 2 * i + (lane >> 5); scr[kk * 33 + (lane & 31)] = W[(size_t)(k0 + kk) * ld + n0 + (lane & 31)]; }
.LBB0_44:
	s_lshl_b32 s27, s6, 1
	s_lshl_b32 s30, s23, 1
	v_or_b32_e32 v21, s27, v3
	v_or_b32_e32 v23, s30, v4
	s_add_i32 s31, s27, 4
	s_add_i32 s33, s30, 4
	s_add_i32 s34, s27, 8
	s_add_i32 s35, s30, 8
	s_add_i32 s36, s27, 12
	s_add_i32 s37, s30, 12
	s_add_i32 s38, s27, 16
	s_add_i32 s39, s30, 16
	s_add_i32 s40, s27, 20
	s_add_i32 s41, s30, 20
	s_add_i32 s42, s27, 24
	s_add_i32 s43, s30, 24
	s_add_i32 s44, s27, 28
	s_add_i32 s45, s30, 28
	v_mad_i64_i32 v[32:33], s[28:29], v23, s17, v[24:25]
	v_mad_i64_i32 v[34:35], s[28:29], v21, s17, v[24:25]
	v_or_b32_e32 v21, s31, v3
	v_or_b32_e32 v23, s33, v4
	v_or_b32_e32 v26, s34, v3
	v_or_b32_e32 v40, s35, v4
	v_or_b32_e32 v46, s36, v3
	v_or_b32_e32 v44, s37, v4
	v_or_b32_e32 v50, s38, v3
	v_or_b32_e32 v48, s39, v4
	v_or_b32_e32 v54, s40, v3
	v_or_b32_e32 v52, s41, v4
	v_or_b32_e32 v58, s42, v3
	v_or_b32_e32 v56, s43, v4
	v_or_b32_e32 v62, s44, v3
	v_or_b32_e32 v60, s45, v4
	v_mad_i64_i32 v[36:37], s[28:29], v23, s17, v[24:25]
	v_mad_i64_i32 v[38:39], s[28:29], v21, s17, v[24:25]
	v_mad_i64_i32 v[40:41], s[28:29], v40, s17, v[24:25]
	v_mad_i64_i32 v[42:43], s[28:29], v26, s17, v[24:25]
	v_mad_i64_i32 v[44:45], s[28:29], v44, s17, v[24:25]
	v_mad_i64_i32 v[46:47], s[28:29], v46, s17, v[24:25]
	v_mad_i64_i32 v[48:49], s[28:29], v48, s17, v[24:25]
	v_mad_i64_i32 v[50:51], s[28:29], v50, s17, v[24:25]
	v_mad_i64_i32 v[52:53], s[28:29], v52, s17, v[24:25]
	v_mad_i64_i32 v[54:55], s[28:29], v54, s17, v[24:25]
	v_mad_i64_i32 v[56:57], s[28:29], v56, s17, v[24:25]
	v_mad_i64_i32 v[58:59], s[28:29], v58, s17, v[24:25]
	v_mad_i64_i32 v[60:61], s[28:29], v60, s17, v[24:25]
	v_mad_i64_i32 v[62:63], s[28:29], v62, s17, v[24:25]
	global_load_dword v21, v[32:33], off nt
	global_load_dword v23, v[34:35], off nt
	global_load_dword v26, v[36:37], off nt
	global_load_dword v64, v[38:39], off nt
	global_load_dword v65, v[40:41], off nt
	global_load_dword v66, v[42:43], off nt
	global_load_dword v67, v[44:45], off nt
	global_load_dword v68, v[46:47], off nt
	global_load_dword v69, v[48:49], off nt
	global_load_dword v70, v[50:51], off nt
	global_load_dword v71, v[52:53], off nt
	global_load_dword v72, v[54:55], off nt
	global_load_dword v73, v[56:57], off nt
	global_load_dword v74, v[58:59], off nt
	global_load_dword v75, v[60:61], off nt
	global_load_dword v76, v[62:63], off nt
	v_or_b32_e32 v34, s27, v1
	v_or_b32_e32 v32, s30, v2
	s_add_i32 s23, s23, 16
	s_add_i32 s6, s6, 16
	s_add_i32 s25, s25, -16
	v_mad_u64_u32 v[32:33], s[28:29], v32, s13, v[8:9]
	v_mad_u64_u32 v[34:35], s[28:29], v34, s13, v[8:9]
	v_or_b32_e32 v33, s31, v1
	v_or_b32_e32 v35, s33, v2
	v_or_b32_e32 v42, s34, v1
	v_or_b32_e32 v40, s35, v2
	v_or_b32_e32 v46, s36, v1
	v_or_b32_e32 v44, s37, v2
	v_or_b32_e32 v50, s38, v1
	v_or_b32_e32 v48, s39, v2
	v_or_b32_e32 v54, s40, v1
	v_or_b32_e32 v52, s41, v2
	v_or_b32_e32 v58, s42, v1
	v_or_b32_e32 v56, s43, v2
	v_or_b32_e32 v62, s44, v1
	v_or_b32_e32 v60, s45, v2
	s_cmp_lg_u32 s25, 0
	v_mad_u64_u32 v[36:37], s[28:29], v35, s13, v[8:9]
	v_mad_u64_u32 v[38:39], s[28:29], v33, s13, v[8:9]
	v_mad_u64_u32 v[40:41], s[28:29], v40, s13, v[8:9]
	v_mad_u64_u32 v[42:43], s[28:29], v42, s13, v[8:9]
	v_mad_u64_u32 v[44:45], s[28:29], v44, s13, v[8:9]
	v_mad_u64_u32 v[46:47], s[28:29], v46, s13, v[8:9]
	v_mad_u64_u32 v[48:49], s[28:29], v48, s13, v[8:9]
	v_mad_u64_u32 v[50:51], s[28:29], v50, s13, v[8:9]
	v_mad_u64_u32 v[52:53], s[28:29], v52, s13, v[8:9]
	v_mad_u64_u32 v[54:55], s[28:29], v54, s13, v[8:9]
	v_mad_u64_u32 v[56:57], s[28:29], v56, s13, v[8:9]
	v_mad_u64_u32 v[58:59], s[28:29], v58, s13, v[8:9]
	v_mad_u64_u32 v[60:61], s[28:29], v60, s13, v[8:9]
	v_mad_u64_u32 v[62:63], s[28:29], v62, s13, v[8:9]
	s_waitcnt vmcnt(15)
	ds_write_b32 v32, v21
	s_waitcnt vmcnt(14)
	ds_write_b32 v34, v23
	s_waitcnt vmcnt(13)
	ds_write_b32 v36, v26
	s_waitcnt vmcnt(12)
	ds_write_b32 v38, v64
	s_waitcnt vmcnt(11)
	ds_write_b32 v40, v65
	s_waitcnt vmcnt(10)
	ds_write_b32 v42, v66
	s_waitcnt vmcnt(9)
	ds_write_b32 v44, v67
	s_waitcnt vmcnt(8)
	ds_write_b32 v46, v68
	s_waitcnt vmcnt(7)
	ds_write_b32 v48, v69
	s_waitcnt vmcnt(6)
	ds_write_b32 v50, v70
	s_waitcnt vmcnt(5)
	ds_write_b32 v52, v71
	s_waitcnt vmcnt(4)
	ds_write_b32 v54, v72
	s_waitcnt vmcnt(3)
	ds_write_b32 v56, v73
	s_waitcnt vmcnt(2)
	ds_write_b32 v58, v74
	s_waitcnt vmcnt(1)
	ds_write_b32 v60, v75
	s_waitcnt vmcnt(0)
	ds_write_b32 v62, v76
	s_cbranch_scc1 .LBB0_44
; #define GAS __attribute__((address_space(1)))
; #define LAS __attribute__((address_space(3)))
; #define LDS_WAIT() asm volatile("s_waitcnt lgkmcnt(0)" ::: "memory")
; __device__ __forceinline__ unsigned pk2(float lo, float hi) { return f2bf(lo) | (f2bf(hi) << 16); }
; __device__ __forceinline__ void p0_transpose_item(const float* W, int ld, int K, int ncols, bf16* WT, LAS float* scr, int item, int lane) {
;     ...
;     LDS_WAIT(); asm volatile("" ::: "memory");
;     const int c = lane & 7;
; #pragma unroll
;     for (int j = 0; j < 4; ++j) { const int n = (lane >> 3) + 8 * j; const LAS float* s = scr + (8 * c) * 33 + n;
;         v4u o; o.x = pk2(s[0 * 33], s[1 * 33]); o.y = pk2(s[2 * 33], s[3 * 33]); o.z = pk2(s[4 * 33], s[5 * 33]); o.w = pk2(s[6 * 33], s[7 * 33]);
;         *(GAS v4u*)(WT + (size_t)(n0 + n) * K + k0 + 8 * c) = o; }
;     LDS_WAIT(); asm volatile("" ::: "memory");
	s_waitcnt lgkmcnt(0)
	ds_read2_b32 v[24:25], v28 offset1:8
	ds_read2_b32 v[38:39], v28 offset0:33 offset1:41
	ds_read2_b32 v[40:41], v28 offset0:66 offset1:74
	ds_read2_b32 v[42:43], v28 offset0:99 offset1:107
	ds_read2_b32 v[44:45], v28 offset0:132 offset1:140
	ds_read2_b32 v[46:47], v28 offset0:165 offset1:173
	s_waitcnt lgkmcnt(5)
	v_bfe_u32 v3, v24, 16, 1
	v_add3_u32 v3, v24, v3, s15
	s_waitcnt lgkmcnt(4)
	v_bfe_u32 v4, v38, 16, 1
	v_lshrrev_b32_e32 v3, 16, v3
	v_add3_u32 v4, v38, v4, s15
	v_and_or_b32 v32, v4, s16, v3
	s_waitcnt lgkmcnt(3)
	v_bfe_u32 v3, v40, 16, 1
	v_add3_u32 v3, v40, v3, s15
	s_waitcnt lgkmcnt(2)
	v_bfe_u32 v4, v42, 16, 1
	ds_read2_b32 v[48:49], v28 offset0:198 offset1:206
	v_lshrrev_b32_e32 v3, 16, v3
	v_add3_u32 v4, v42, v4, s15
	ds_read2_b32 v[50:51], v28 offset0:231 offset1:239
	v_and_or_b32 v33, v4, s16, v3
	s_waitcnt lgkmcnt(3)
	v_bfe_u32 v3, v44, 16, 1
	v_add3_u32 v3, v44, v3, s15
	s_waitcnt lgkmcnt(2)
	v_bfe_u32 v4, v46, 16, 1
	v_lshrrev_b32_e32 v3, 16, v3
	v_add3_u32 v4, v46, v4, s15
	v_and_or_b32 v34, v4, s16, v3
	s_waitcnt lgkmcnt(1)
	v_bfe_u32 v3, v48, 16, 1
	v_add3_u32 v3, v48, v3, s15
	s_waitcnt lgkmcnt(0)
	v_bfe_u32 v4, v50, 16, 1
	v_lshrrev_b32_e32 v3, 16, v3
	v_add3_u32 v4, v50, v4, s15
	v_or_b32_e32 v52, s22, v27
	s_ashr_i32 s25, s24, 31
	v_and_or_b32 v35, v4, s16, v3
	v_ashrrev_i32_e32 v53, 31, v52
	v_bfe_u32 v3, v25, 16, 1
	v_lshl_add_u64 v[36:37], s[24:25], 1, v[18:19]
	v_lshlrev_b64 v[52:53], 11, v[52:53]
	v_add3_u32 v3, v25, v3, s15
	v_bfe_u32 v4, v39, 16, 1
	v_lshl_add_u64 v[52:53], v[36:37], 0, v[52:53]
	v_lshrrev_b32_e32 v3, 16, v3
	v_add3_u32 v4, v39, v4, s15
	global_store_dwordx4 v[52:53], v[32:35], off
	v_or_b32_e32 v24, s22, v29
	v_ashrrev_i32_e32 v25, 31, v24
	v_and_or_b32 v32, v4, s16, v3
	v_bfe_u32 v3, v41, 16, 1
	v_add3_u32 v3, v41, v3, s15
	v_bfe_u32 v4, v43, 16, 1
	v_lshrrev_b32_e32 v3, 16, v3
	v_add3_u32 v4, v43, v4, s15
	v_and_or_b32 v33, v4, s16, v3
	v_bfe_u32 v3, v45, 16, 1
	v_add3_u32 v3, v45, v3, s15
	v_bfe_u32 v4, v47, 16, 1
	v_lshrrev_b32_e32 v3, 16, v3
	v_add3_u32 v4, v47, v4, s15
	v_and_or_b32 v34, v4, s16, v3
	v_bfe_u32 v3, v49, 16, 1
	v_add3_u32 v3, v49, v3, s15
	v_bfe_u32 v4, v51, 16, 1
	v_lshrrev_b32_e32 v3, 16, v3
	v_add3_u32 v4, v51, v4, s15
	v_lshlrev_b64 v[24:25], 11, v[24:25]
	v_and_or_b32 v35, v4, s16, v3
	ds_read2_b32 v[38:39], v28 offset0:16 offset1:24
	v_lshl_add_u64 v[24:25], v[36:37], 0, v[24:25]
	global_store_dwordx4 v[24:25], v[32:35], off
	ds_read2_b32 v[24:25], v28 offset0:49 offset1:57
	ds_read2_b32 v[40:41], v28 offset0:82 offset1:90
	ds_read2_b32 v[42:43], v28 offset0:115 offset1:123
	s_waitcnt lgkmcnt(3)
	v_bfe_u32 v3, v38, 16, 1
	v_add3_u32 v3, v38, v3, s15
	s_waitcnt lgkmcnt(2)
	v_bfe_u32 v4, v24, 16, 1
	ds_read2_b32 v[44:45], v28 offset0:148 offset1:156
	v_lshrrev_b32_e32 v3, 16, v3
	v_add3_u32 v4, v24, v4, s15
	ds_read2_b32 v[46:47], v28 offset0:181 offset1:189
	v_and_or_b32 v32, v4, s16, v3
	s_waitcnt lgkmcnt(3)
	v_bfe_u32 v3, v40, 16, 1
	v_add3_u32 v3, v40, v3, s15
	s_waitcnt lgkmcnt(2)
	v_bfe_u32 v4, v42, 16, 1
	ds_read2_b32 v[48:49], v28 offset0:214 offset1:222
	v_lshrrev_b32_e32 v3, 16, v3
	v_add3_u32 v4, v42, v4, s15
	ds_read2_b32 v[50:51], v28 offset0:247 offset1:255
	v_and_or_b32 v33, v4, s16, v3
	s_waitcnt lgkmcnt(3)
	v_bfe_u32 v3, v44, 16, 1
	v_add3_u32 v3, v44, v3, s15
	s_waitcnt lgkmcnt(2)
	v_bfe_u32 v4, v46, 16, 1
	v_lshrrev_b32_e32 v3, 16, v3
	v_add3_u32 v4, v46, v4, s15
	v_and_or_b32 v34, v4, s16, v3
	s_waitcnt lgkmcnt(1)
	v_bfe_u32 v3, v48, 16, 1
	v_add3_u32 v3, v48, v3, s15
	s_waitcnt lgkmcnt(0)
	v_bfe_u32 v4, v50, 16, 1
	v_lshrrev_b32_e32 v3, 16, v3
	v_add3_u32 v4, v50, v4, s15
	v_or_b32_e32 v52, s22, v30
	v_and_or_b32 v35, v4, s16, v3
	v_ashrrev_i32_e32 v53, 31, v52
	v_bfe_u32 v3, v39, 16, 1
	v_lshlrev_b64 v[52:53], 11, v[52:53]
	v_add3_u32 v3, v39, v3, s15
	v_bfe_u32 v4, v25, 16, 1
	v_lshl_add_u64 v[52:53], v[36:37], 0, v[52:53]
	v_lshrrev_b32_e32 v3, 16, v3
	v_add3_u32 v4, v25, v4, s15
	global_store_dwordx4 v[52:53], v[32:35], off
	v_or_b32_e32 v24, s22, v31
	v_ashrrev_i32_e32 v25, 31, v24
	v_and_or_b32 v32, v4, s16, v3
	v_bfe_u32 v3, v41, 16, 1
	v_add3_u32 v3, v41, v3, s15
	v_bfe_u32 v4, v43, 16, 1
	v_lshrrev_b32_e32 v3, 16, v3
	v_add3_u32 v4, v43, v4, s15
	v_and_or_b32 v33, v4, s16, v3
	v_bfe_u32 v3, v45, 16, 1
	v_add3_u32 v3, v45, v3, s15
	v_bfe_u32 v4, v47, 16, 1
	v_lshrrev_b32_e32 v3, 16, v3
	v_add3_u32 v4, v47, v4, s15
	v_and_or_b32 v34, v4, s16, v3
	v_bfe_u32 v3, v49, 16, 1
	v_add3_u32 v3, v49, v3, s15
	v_bfe_u32 v4, v51, 16, 1
	v_lshrrev_b32_e32 v3, 16, v3
	v_add3_u32 v4, v51, v4, s15
	v_lshlrev_b64 v[24:25], 11, v[24:25]
	v_and_or_b32 v35, v4, s16, v3
	v_lshl_add_u64 v[24:25], v[36:37], 0, v[24:25]
	global_store_dwordx4 v[24:25], v[32:35], off
	s_waitcnt lgkmcnt(0)
	s_branch .LBB0_13

; #define GAS __attribute__((address_space(1)))
; __global__ void __launch_bounds__(NWAVES * 64, 2) hybrid_fwd(Args args) {
;     ...
;         for (int m = 2 * gw; m < MTOK; m += 2 * NGW) {
;             f32x4 xv[2][4]; v2u ow[2][4]; float sp[2];
; #pragma unroll
;             for (int r = 0; r < 2; ++r) { sp[r] = (lane < 16) ? ((const GAS float*)SSP)[(size_t)(m + r) * 16 + lane] : 0.f;
;                 const GAS f32x4* xr = (const GAS f32x4*)(xg_ + (size_t)(m + r) * D) + lane; const GAS v2u* orow = (const GAS v2u*)(OUTB + (size_t)(m + r) * D) + lane;
; #pragma unroll
;                 for (int j = 0; j < 4; ++j) { xv[r][j] = xr[64 * j]; ow[r][j] = orow[64 * j]; } }
; #pragma unroll
;             for (int r = 0; r < 2; ++r) { const float rs = 1.f / sqrtf(wave_sum(sp[r], lane) * (1.f / D) + RMS_EPS);
;                 const GAS f32x4* gr = (const GAS f32x4*)gpost_ + lane; GAS f32x4* yr = (GAS f32x4*)(outg_ + (size_t)(m + r) * D) + lane;
; #pragma unroll
;                 for (int j = 0; j < 4; ++j) { const f32x4 gg = gr[64 * j]; f32x4 y;
;                     y.x = xv[r][j].x + pg8::bf_lo(ow[r][j].x) * rs * gg.x; y.y = xv[r][j].y + pg8::bf_hi(ow[r][j].x) * rs * gg.y; y.z = xv[r][j].z + pg8::bf_lo(ow[r][j].y) * rs * gg.z; y.w = xv[r][j].w + pg8::bf_hi(ow[r][j].y) * rs * gg.w;
;                     __builtin_nontemporal_store(y, &yr[64 * j]); } }
.LBB0_1028:
	s_or_b64 exec, exec, s[2:3]
	global_load_dwordx4 v[54:57], v[30:31], off
	s_waitcnt vmcnt(9)
	ds_bpermute_b32 v6, v44, v8
	v_add_co_u32_e32 v36, vcc, 0x1000, v2
	s_waitcnt vmcnt(4)
	v_lshlrev_b32_e32 v64, 16, v4
	v_and_b32_e32 v65, 0xffff0000, v4
	s_waitcnt lgkmcnt(0)
	v_add_f32_e32 v6, v8, v6
	ds_bpermute_b32 v7, v45, v6
	v_addc_co_u32_e32 v37, vcc, 0, v3, vcc
	v_add_co_u32_e32 v68, vcc, 0xbc00000, v0
	s_waitcnt lgkmcnt(0)
	v_add_f32_e32 v6, v6, v7
	ds_bpermute_b32 v7, v46, v6
	v_addc_co_u32_e32 v69, vcc, 0, v1, vcc
	v_lshlrev_b32_e32 v66, 16, v5
	v_and_b32_e32 v67, 0xffff0000, v5
	s_waitcnt lgkmcnt(0)
	v_add_f32_e32 v2, v6, v7
	ds_bpermute_b32 v6, v47, v2
	v_lshl_add_u64 v[62:63], s[16:17], 0, v[28:29]
	s_add_i32 s6, s6, s8
	s_add_u32 s12, s12, s14
	s_addc_u32 s13, s13, s15
	s_waitcnt lgkmcnt(0)
	v_add_f32_e32 v2, v2, v6
	ds_bpermute_b32 v4, v48, v2
	s_add_u32 s16, s16, s14
	s_addc_u32 s17, s17, s15
	v_lshl_add_u64 v[32:33], v[32:33], 0, s[10:11]
	s_cmp_gt_i32 s6, 0xffff
	s_waitcnt lgkmcnt(0)
	v_add_f32_e32 v2, v2, v4
	ds_bpermute_b32 v3, v49, v2
	v_lshl_add_u64 v[34:35], v[34:35], 0, s[18:19]
	s_waitcnt lgkmcnt(0)
	v_add_f32_e32 v0, v2, v3
	v_fmamk_f32 v0, v0, 0x3a800000, v50
	v_mul_f32_e32 v1, 0x4f800000, v0
	v_cmp_gt_f32_e32 vcc, s9, v0
	s_nop 1
	v_cndmask_b32_e32 v53, v0, v1, vcc
	v_sqrt_f32_e32 v70, v53
	global_load_dwordx4 v[58:61], v[36:37], off nt
	global_load_dwordx4 v[8:11], v[36:37], off offset:1024 nt
	global_load_dwordx4 v[4:7], v[36:37], off offset:2048 nt
	global_load_dwordx4 v[0:3], v[36:37], off offset:3072 nt
	v_add_u32_e32 v36, -1, v70
	v_add_u32_e32 v37, 1, v70
	v_fma_f32 v71, -v36, v70, v53
	v_fma_f32 v72, -v37, v70, v53
	v_cmp_ge_f32_e64 s[2:3], 0, v71
	s_nop 1
	v_cndmask_b32_e64 v36, v70, v36, s[2:3]
	v_cmp_lt_f32_e64 s[2:3], 0, v72
	s_nop 1
	v_cndmask_b32_e64 v36, v36, v37, s[2:3]
	v_mul_f32_e32 v37, 0x37800000, v36
	v_cndmask_b32_e32 v36, v36, v37, vcc
	v_cmp_class_f32_e32 vcc, v53, v51
	s_nop 1
	v_cndmask_b32_e32 v53, v36, v53, vcc
	v_div_scale_f32 v76, s[2:3], v53, v53, 1.0
	v_rcp_f32_e32 v77, v76
	global_load_dwordx2 v[70:71], v[68:69], off offset:2048 nt
	global_load_dwordx2 v[72:73], v[68:69], off offset:2560 nt
	global_load_dwordx2 v[74:75], v[68:69], off offset:3072 nt
	global_load_dwordx2 v[36:37], v[68:69], off offset:3584 nt
	v_div_scale_f32 v68, vcc, 1.0, v53, 1.0
	v_fma_f32 v69, -v76, v77, 1.0
	v_fmac_f32_e32 v77, v69, v77
	v_mul_f32_e32 v69, v68, v77
	v_fma_f32 v78, -v76, v69, v68
	v_fmac_f32_e32 v69, v78, v77
	v_fma_f32 v68, -v76, v69, v68
	v_div_fmas_f32 v68, v68, v77, v69
	v_div_fixup_f32 v68, v68, v53, 1.0
	v_pk_mul_f32 v[64:65], v[68:69], v[64:65] op_sel_hi:[0,1]
	v_pk_mul_f32 v[66:67], v[68:69], v[66:67] op_sel_hi:[0,1]
	s_waitcnt vmcnt(8)
	v_pk_fma_f32 v[24:25], v[54:55], v[64:65], v[24:25]
	v_pk_fma_f32 v[26:27], v[56:57], v[66:67], v[26:27]
	global_store_dwordx4 v[62:63], v[24:27], off nt
	global_load_dwordx4 v[24:27], v[30:31], off offset:1024
	v_lshlrev_b32_e32 v54, 16, v42
	v_and_b32_e32 v55, 0xffff0000, v42
	v_lshlrev_b32_e32 v42, 16, v43
	v_and_b32_e32 v43, 0xffff0000, v43
	v_pk_mul_f32 v[54:55], v[68:69], v[54:55] op_sel_hi:[0,1]
	v_pk_mul_f32 v[42:43], v[68:69], v[42:43] op_sel_hi:[0,1]
	s_waitcnt vmcnt(0)
	v_pk_fma_f32 v[20:21], v[24:25], v[54:55], v[20:21]
	v_pk_fma_f32 v[22:23], v[26:27], v[42:43], v[22:23]
	global_store_dwordx4 v[62:63], v[20:23], off offset:1024 nt
	global_load_dwordx4 v[20:23], v[30:31], off offset:2048
	v_lshlrev_b32_e32 v24, 16, v40
	v_and_b32_e32 v25, 0xffff0000, v40
	v_lshlrev_b32_e32 v26, 16, v41
	v_and_b32_e32 v27, 0xffff0000, v41
	v_pk_mul_f32 v[24:25], v[68:69], v[24:25] op_sel_hi:[0,1]
	v_pk_mul_f32 v[26:27], v[68:69], v[26:27] op_sel_hi:[0,1]
	s_waitcnt vmcnt(0)
; #define GAS __attribute__((address_space(1)))
; __global__ void __launch_bounds__(NWAVES * 64, 2) hybrid_fwd(Args args) {
;     ...
;             for (int r = 0; r < 2; ++r) { const float rs = 1.f / sqrtf(wave_sum(sp[r], lane) * (1.f / D) + RMS_EPS);
;                 const GAS f32x4* gr = (const GAS f32x4*)gpost_ + lane; GAS f32x4* yr = (GAS f32x4*)(outg_ + (size_t)(m + r) * D) + lane;
; #pragma unroll
;                 for (int j = 0; j < 4; ++j) { const f32x4 gg = gr[64 * j]; f32x4 y;
;                     y.x = xv[r][j].x + pg8::bf_lo(ow[r][j].x) * rs * gg.x; y.y = xv[r][j].y + pg8::bf_hi(ow[r][j].x) * rs * gg.y; y.z = xv[r][j].z + pg8::bf_lo(ow[r][j].y) * rs * gg.z; y.w = xv[r][j].w + pg8::bf_hi(ow[r][j].y) * rs * gg.w;
;                     __builtin_nontemporal_store(y, &yr[64 * j]); } }
	v_pk_fma_f32 v[16:17], v[20:21], v[24:25], v[16:17]
	v_pk_fma_f32 v[18:19], v[22:23], v[26:27], v[18:19]
	global_store_dwordx4 v[62:63], v[16:19], off offset:2048 nt
	global_load_dwordx4 v[16:19], v[30:31], off offset:3072
	v_lshlrev_b32_e32 v20, 16, v38
	v_and_b32_e32 v21, 0xffff0000, v38
	v_lshlrev_b32_e32 v22, 16, v39
	v_and_b32_e32 v23, 0xffff0000, v39
	v_pk_mul_f32 v[20:21], v[68:69], v[20:21] op_sel_hi:[0,1]
	v_pk_mul_f32 v[22:23], v[68:69], v[22:23] op_sel_hi:[0,1]
	ds_bpermute_b32 v24, v44, v52
	s_waitcnt vmcnt(0)
	v_pk_fma_f32 v[12:13], v[16:17], v[20:21], v[12:13]
	v_pk_fma_f32 v[14:15], v[18:19], v[22:23], v[14:15]
	global_store_dwordx4 v[62:63], v[12:15], off offset:3072 nt
	global_load_dwordx4 v[12:15], v[30:31], off
	s_waitcnt lgkmcnt(0)
	v_add_f32_e32 v16, v52, v24
	ds_bpermute_b32 v17, v45, v16
	s_waitcnt lgkmcnt(0)
	v_add_f32_e32 v16, v16, v17
	ds_bpermute_b32 v17, v46, v16
	s_waitcnt lgkmcnt(0)
	v_add_f32_e32 v16, v16, v17
	ds_bpermute_b32 v17, v47, v16
	s_waitcnt lgkmcnt(0)
	v_add_f32_e32 v16, v16, v17
	ds_bpermute_b32 v17, v48, v16
	s_waitcnt lgkmcnt(0)
	v_add_f32_e32 v16, v16, v17
	ds_bpermute_b32 v17, v49, v16
	s_waitcnt lgkmcnt(0)
	v_add_f32_e32 v16, v16, v17
	v_fmamk_f32 v16, v16, 0x3a800000, v50
	v_mul_f32_e32 v17, 0x4f800000, v16
	v_cmp_gt_f32_e32 vcc, s9, v16
	s_nop 1
	v_cndmask_b32_e32 v16, v16, v17, vcc
	v_sqrt_f32_e32 v17, v16
	s_nop 0
	v_add_u32_e32 v18, -1, v17
	v_add_u32_e32 v19, 1, v17
	v_fma_f32 v20, -v18, v17, v16
	v_fma_f32 v21, -v19, v17, v16
	v_cmp_ge_f32_e64 s[2:3], 0, v20
	s_nop 1
	v_cndmask_b32_e64 v17, v17, v18, s[2:3]
	v_cmp_lt_f32_e64 s[2:3], 0, v21
	s_nop 1
	v_cndmask_b32_e64 v17, v17, v19, s[2:3]
	v_mul_f32_e32 v18, 0x37800000, v17
	v_cndmask_b32_e32 v17, v17, v18, vcc
	v_cmp_class_f32_e32 vcc, v16, v51
	s_nop 1
	v_cndmask_b32_e32 v18, v17, v16, vcc
	v_div_scale_f32 v19, s[2:3], v18, v18, 1.0
	v_rcp_f32_e32 v20, v19
	v_add_co_u32_e32 v16, vcc, s7, v62
	v_fma_f32 v22, -v19, v20, 1.0
	s_nop 0
	v_addc_co_u32_e32 v17, vcc, 0, v63, vcc
	v_div_scale_f32 v21, vcc, 1.0, v18, 1.0
	v_fmac_f32_e32 v20, v22, v20
	v_mul_f32_e32 v22, v21, v20
	v_fma_f32 v23, -v19, v22, v21
	v_fmac_f32_e32 v22, v23, v20
	v_fma_f32 v19, -v19, v22, v21
	v_div_fmas_f32 v19, v19, v20, v22
	v_div_fixup_f32 v18, v19, v18, 1.0
	v_lshlrev_b32_e32 v20, 16, v70
	v_and_b32_e32 v21, 0xffff0000, v70
	v_lshlrev_b32_e32 v22, 16, v71
	v_and_b32_e32 v23, 0xffff0000, v71
	v_pk_mul_f32 v[20:21], v[18:19], v[20:21] op_sel_hi:[0,1]
	v_pk_mul_f32 v[22:23], v[18:19], v[22:23] op_sel_hi:[0,1]
	s_waitcnt vmcnt(0)
	v_pk_fma_f32 v[12:13], v[12:13], v[20:21], v[58:59]
	v_pk_fma_f32 v[14:15], v[14:15], v[22:23], v[60:61]
	global_store_dwordx4 v[16:17], v[12:15], off nt
	global_load_dwordx4 v[12:15], v[30:31], off offset:1024
	v_lshlrev_b32_e32 v20, 16, v72
	v_and_b32_e32 v21, 0xffff0000, v72
	v_lshlrev_b32_e32 v22, 16, v73
	v_and_b32_e32 v23, 0xffff0000, v73
	v_pk_mul_f32 v[20:21], v[18:19], v[20:21] op_sel_hi:[0,1]
	v_pk_mul_f32 v[22:23], v[18:19], v[22:23] op_sel_hi:[0,1]
	s_waitcnt vmcnt(0)
	v_pk_fma_f32 v[8:9], v[12:13], v[20:21], v[8:9]
	v_pk_fma_f32 v[10:11], v[14:15], v[22:23], v[10:11]
	global_store_dwordx4 v[16:17], v[8:11], off offset:1024 nt
	global_load_dwordx4 v[8:11], v[30:31], off offset:2048
	v_lshlrev_b32_e32 v12, 16, v74
	v_and_b32_e32 v13, 0xffff0000, v74
	v_lshlrev_b32_e32 v14, 16, v75
	v_and_b32_e32 v15, 0xffff0000, v75
	v_pk_mul_f32 v[12:13], v[18:19], v[12:13] op_sel_hi:[0,1]
	v_pk_mul_f32 v[14:15], v[18:19], v[14:15] op_sel_hi:[0,1]
	s_waitcnt vmcnt(0)
	v_pk_fma_f32 v[4:5], v[8:9], v[12:13], v[4:5]
	v_pk_fma_f32 v[6:7], v[10:11], v[14:15], v[6:7]
	global_store_dwordx4 v[16:17], v[4:7], off offset:2048 nt
	global_load_dwordx4 v[4:7], v[30:31], off offset:3072
	v_lshlrev_b32_e32 v8, 16, v36
	v_and_b32_e32 v9, 0xffff0000, v36
	v_lshlrev_b32_e32 v10, 16, v37
	v_and_b32_e32 v11, 0xffff0000, v37
	v_pk_mul_f32 v[8:9], v[18:19], v[8:9] op_sel_hi:[0,1]
	v_pk_mul_f32 v[10:11], v[18:19], v[10:11] op_sel_hi:[0,1]
	s_waitcnt vmcnt(0)
	v_pk_fma_f32 v[0:1], v[4:5], v[8:9], v[0:1]
	v_pk_fma_f32 v[2:3], v[6:7], v[10:11], v[2:3]
	global_store_dwordx4 v[16:17], v[0:3], off offset:3072 nt
	s_cbranch_scc1 .LBB0_1033

; #define GAS __attribute__((address_space(1)))
; __global__ void __launch_bounds__(NWAVES * 64, 2) hybrid_fwd(Args args) {
;     ...
;         for (int m = 2 * gw; m < MTOK; m += 2 * NGW) {
;             f32x4 xv[2][4]; v2u ow[2][4]; float sp[2];
; #pragma unroll
;             for (int r = 0; r < 2; ++r) { sp[r] = (lane < 16) ? ((const GAS float*)SSP)[(size_t)(m + r) * 16 + lane] : 0.f;
;                 const GAS f32x4* xr = (const GAS f32x4*)(xg_ + (size_t)(m + r) * D) + lane; const GAS v2u* orow = (const GAS v2u*)(OUTB + (size_t)(m + r) * D) + lane;
; #pragma unroll
;                 for (int j = 0; j < 4; ++j) { xv[r][j] = xr[64 * j]; ow[r][j] = orow[64 * j]; } }
.LBB0_1031:
	s_or_b64 exec, exec, s[2:3]
	v_lshl_add_u64 v[0:1], s[4:5], 0, v[34:35]
	v_lshl_add_u64 v[2:3], s[12:13], 0, v[28:29]
	v_add_co_u32_e32 v10, vcc, 0xbc00000, v0
	v_mov_b32_e32 v52, 0
	s_nop 0
	v_addc_co_u32_e32 v11, vcc, 0, v1, vcc
	global_load_dwordx4 v[24:27], v[2:3], off nt
	global_load_dwordx4 v[20:23], v[2:3], off offset:1024 nt
	global_load_dwordx4 v[16:19], v[2:3], off offset:2048 nt
	global_load_dwordx4 v[12:15], v[2:3], off offset:3072 nt
	global_load_dwordx2 v[4:5], v[10:11], off nt
	global_load_dwordx2 v[42:43], v[10:11], off offset:512 nt
	global_load_dwordx2 v[40:41], v[10:11], off offset:1024 nt
	global_load_dwordx2 v[38:39], v[10:11], off offset:1536 nt
	s_and_saveexec_b64 s[2:3], s[0:1]
	s_cbranch_execz .LBB0_1028
	v_add_co_u32_e32 v6, vcc, 0x3800000, v6
	s_nop 1
	v_addc_co_u32_e32 v7, vcc, 0, v7, vcc
	global_load_dword v52, v[6:7], off offset:64
	s_branch .LBB0_1028
